# GEMM loops: per-segment s_setprio flips removed, one static s_setprio 1 for waves 4-7 at kernel entry
# speedup vs baseline: 1.0218x; 1.0218x over previous
_Z4mega6Params:
	s_load_dwordx8 s[88:95], s[0:1], 0xa0
	s_load_dwordx8 s[4:11], s[0:1], 0x80
	s_load_dword s96, s[0:1], 0xc0
	s_mov_b32 s97, s2
	s_add_u32 s2, s0, 0xc0
	s_addc_u32 s3, s1, 0
	s_waitcnt lgkmcnt(0)
	v_readfirstlane_b32 s98, v0
	s_nop 3
	s_cmpk_lt_u32 s98, 0x100
	s_cbranch_scc1 .Lprio_skip
	s_setprio 1
.Lprio_skip:
	v_writelane_b32 v255, s4, 0
	s_nop 1
	v_writelane_b32 v255, s5, 1
	v_writelane_b32 v255, s6, 2
	v_writelane_b32 v255, s7, 3
	v_writelane_b32 v255, s8, 4
	v_writelane_b32 v255, s9, 5
	v_writelane_b32 v255, s10, 6
	v_writelane_b32 v255, s11, 7
	v_writelane_b32 v255, s2, 8
	v_cmp_eq_u32_e64 s[4:5], 0, v0
	s_nop 0
	v_writelane_b32 v255, s3, 9
	s_mov_b64 s[2:3], exec
	v_writelane_b32 v255, s4, 10
	s_nop 1
	v_writelane_b32 v255, s5, 11
	s_and_b64 s[4:5], s[2:3], s[4:5]
	s_mov_b64 exec, s[4:5]
	s_cbranch_execz .LBB0_2
	s_add_i32 s4, 0, 0x20000
	v_mov_b32_e32 v1, 0
	v_mov_b32_e32 v2, s4
	s_add_i32 s4, 0, 0x20004
	ds_write_b32 v2, v1
	v_mov_b32_e32 v2, s4
	ds_write_b32 v2, v1

.LBB0_257:
	s_or_b64 exec, exec, s[52:53]
	s_add_i32 s58, s54, 2
	v_add_u32_e32 v3, s67, v190
	s_add_u32 s52, s16, s6
	ds_read_b128 v[154:157], v3
	ds_read_b128 v[158:161], v3 offset:1024
	ds_read_b128 v[162:165], v3 offset:2048
	ds_read_b128 v[166:169], v3 offset:3072
	s_addc_u32 s53, s17, s7
	s_add_u32 s52, s52, 0x100
	s_addc_u32 s53, s53, 0
	s_add_u32 s59, s56, s6
	s_addc_u32 s55, s57, s7
	s_cmp_eq_u32 s65, s54
	s_cselect_b32 s53, s33, s53
	s_cselect_b32 s52, s45, s52
	s_cselect_b32 s55, s49, s55
	s_cselect_b32 s54, s48, s59
	v_lshl_add_u64 v[174:175], v[150:151], 0, s[6:7]
	s_add_i32 m0, s39, 0xc000
	ds_read_b128 v[170:173], v192
	ds_read_b128 v[204:207], v192 offset:1024
	ds_read_b128 v[208:211], v192 offset:2048
	ds_read_b128 v[212:215], v192 offset:3072
	ds_read_b128 v[216:219], v192 offset:4096
	ds_read_b128 v[220:223], v192 offset:5120
	ds_read_b128 v[224:227], v192 offset:6144
	ds_read_b128 v[228:231], v192 offset:7168
	global_load_lds_dwordx4 v[174:175], off
	v_lshl_add_u64 v[174:175], v[152:153], 0, s[6:7]
	s_add_i32 m0, s39, 0xe000
	s_nop 0
	global_load_lds_dwordx4 v[174:175], off
	s_waitcnt lgkmcnt(8)
	s_barrier
	s_waitcnt lgkmcnt(0)
	s_waitcnt lgkmcnt(0)
	v_mfma_f32_16x16x32_bf16 v[130:133], v[154:157], v[170:173], v[130:133]
	v_mfma_f32_16x16x32_bf16 v[126:129], v[162:165], v[170:173], v[126:129]
	v_mfma_f32_16x16x32_bf16 v[122:125], v[154:157], v[208:211], v[122:125]
	v_mfma_f32_16x16x32_bf16 v[118:121], v[162:165], v[208:211], v[118:121]
	v_mfma_f32_16x16x32_bf16 v[114:117], v[154:157], v[216:219], v[114:117]
	v_mfma_f32_16x16x32_bf16 v[110:113], v[162:165], v[216:219], v[110:113]
	v_mfma_f32_16x16x32_bf16 v[106:109], v[154:157], v[224:227], v[106:109]
	v_mfma_f32_16x16x32_bf16 v[98:101], v[162:165], v[224:227], v[98:101]
	v_mfma_f32_16x16x32_bf16 v[130:133], v[158:161], v[204:207], v[130:133]
	v_mfma_f32_16x16x32_bf16 v[126:129], v[166:169], v[204:207], v[126:129]
	v_mfma_f32_16x16x32_bf16 v[122:125], v[158:161], v[212:215], v[122:125]
	v_mfma_f32_16x16x32_bf16 v[118:121], v[166:169], v[212:215], v[118:121]
	v_mfma_f32_16x16x32_bf16 v[114:117], v[158:161], v[220:223], v[114:117]
	v_mfma_f32_16x16x32_bf16 v[110:113], v[166:169], v[220:223], v[110:113]
	v_mfma_f32_16x16x32_bf16 v[106:109], v[158:161], v[228:231], v[106:109]
	v_mfma_f32_16x16x32_bf16 v[98:101], v[166:169], v[228:231], v[98:101]
	s_barrier
	s_add_i32 s59, s67, s37
	v_add_u32_e32 v3, s68, v190
	v_lshl_add_u64 v[174:175], s[54:55], 0, v[138:139]
	s_mov_b32 m0, s59
	ds_read_b128 v[232:235], v3
	ds_read_b128 v[236:239], v3 offset:1024
	ds_read_b128 v[240:243], v3 offset:2048
	ds_read_b128 v[244:247], v3 offset:3072
	global_load_lds_dwordx4 v[174:175], off
	v_lshl_add_u64 v[248:249], s[54:55], 0, v[142:143]
	s_add_i32 m0, s59, 0x2000
	s_nop 0
	global_load_lds_dwordx4 v[248:249], off
	s_barrier
	s_waitcnt lgkmcnt(0)
	s_waitcnt lgkmcnt(0)
	v_mfma_f32_16x16x32_bf16 v[102:105], v[232:235], v[170:173], v[102:105]
	v_mfma_f32_16x16x32_bf16 v[94:97], v[240:243], v[170:173], v[94:97]
	v_mfma_f32_16x16x32_bf16 v[90:93], v[232:235], v[208:211], v[90:93]
	v_mfma_f32_16x16x32_bf16 v[86:89], v[240:243], v[208:211], v[86:89]
	v_mfma_f32_16x16x32_bf16 v[82:85], v[232:235], v[216:219], v[82:85]
	v_mfma_f32_16x16x32_bf16 v[78:81], v[240:243], v[216:219], v[78:81]
	v_mfma_f32_16x16x32_bf16 v[74:77], v[232:235], v[224:227], v[74:77]
	v_mfma_f32_16x16x32_bf16 v[70:73], v[240:243], v[224:227], v[70:73]
	v_mfma_f32_16x16x32_bf16 v[102:105], v[236:239], v[204:207], v[102:105]
	v_mfma_f32_16x16x32_bf16 v[94:97], v[244:247], v[204:207], v[94:97]
	v_mfma_f32_16x16x32_bf16 v[90:93], v[236:239], v[212:215], v[90:93]
	v_mfma_f32_16x16x32_bf16 v[86:89], v[244:247], v[212:215], v[86:89]
	v_mfma_f32_16x16x32_bf16 v[82:85], v[236:239], v[220:223], v[82:85]
	v_mfma_f32_16x16x32_bf16 v[78:81], v[244:247], v[220:223], v[78:81]
	v_mfma_f32_16x16x32_bf16 v[74:77], v[236:239], v[228:231], v[74:77]
	v_mfma_f32_16x16x32_bf16 v[70:73], v[244:247], v[228:231], v[70:73]
	s_mov_b32 m0, s39
	v_lshl_add_u64 v[250:251], s[52:53], 0, v[136:137]
	s_barrier
	ds_read_b128 v[170:173], v192 offset:16384
	ds_read_b128 v[204:207], v192 offset:17408
	ds_read_b128 v[208:211], v192 offset:18432
	ds_read_b128 v[212:215], v192 offset:19456
	ds_read_b128 v[216:219], v192 offset:20480
	ds_read_b128 v[220:223], v192 offset:21504
	ds_read_b128 v[224:227], v192 offset:22528
	ds_read_b128 v[228:231], v192 offset:23552
	global_load_lds_dwordx4 v[250:251], off
	v_lshl_add_u64 v[252:253], s[52:53], 0, v[140:141]
	s_mov_b32 m0, s41
	s_nop 0
	global_load_lds_dwordx4 v[252:253], off
	s_barrier
	s_waitcnt lgkmcnt(0)
	s_waitcnt lgkmcnt(0)
	v_mfma_f32_16x16x32_bf16 v[66:69], v[154:157], v[170:173], v[66:69]
	v_mfma_f32_16x16x32_bf16 v[62:65], v[162:165], v[170:173], v[62:65]
	v_mfma_f32_16x16x32_bf16 v[58:61], v[154:157], v[208:211], v[58:61]
	v_mfma_f32_16x16x32_bf16 v[54:57], v[162:165], v[208:211], v[54:57]
	v_mfma_f32_16x16x32_bf16 v[50:53], v[154:157], v[216:219], v[50:53]
	v_mfma_f32_16x16x32_bf16 v[46:49], v[162:165], v[216:219], v[46:49]
	v_mfma_f32_16x16x32_bf16 v[42:45], v[154:157], v[224:227], v[42:45]
	v_mfma_f32_16x16x32_bf16 v[38:41], v[162:165], v[224:227], v[38:41]
	v_mfma_f32_16x16x32_bf16 v[66:69], v[158:161], v[204:207], v[66:69]
	v_mfma_f32_16x16x32_bf16 v[62:65], v[166:169], v[204:207], v[62:65]
	v_mfma_f32_16x16x32_bf16 v[58:61], v[158:161], v[212:215], v[58:61]
	v_mfma_f32_16x16x32_bf16 v[54:57], v[166:169], v[212:215], v[54:57]
	v_mfma_f32_16x16x32_bf16 v[50:53], v[158:161], v[220:223], v[50:53]
	v_mfma_f32_16x16x32_bf16 v[46:49], v[166:169], v[220:223], v[46:49]
	v_mfma_f32_16x16x32_bf16 v[42:45], v[158:161], v[228:231], v[42:45]
	v_mfma_f32_16x16x32_bf16 v[38:41], v[166:169], v[228:231], v[38:41]
	s_barrier
	s_add_u32 s54, s54, s10
	s_addc_u32 s55, s55, s11
	s_add_i32 s59, s68, s37
	v_lshl_add_u64 v[180:181], s[54:55], 0, v[138:139]
	s_mov_b32 m0, s59
	v_lshl_add_u64 v[184:185], s[54:55], 0, v[142:143]
	global_load_lds_dwordx4 v[180:181], off
	s_add_i32 m0, s59, 0x2000
	s_nop 0
	global_load_lds_dwordx4 v[184:185], off
	s_waitcnt vmcnt(6)
	s_barrier
	v_mfma_f32_16x16x32_bf16 v[34:37], v[232:235], v[170:173], v[34:37]
	v_mfma_f32_16x16x32_bf16 v[30:33], v[240:243], v[170:173], v[30:33]
	v_mfma_f32_16x16x32_bf16 v[26:29], v[232:235], v[208:211], v[26:29]
	v_mfma_f32_16x16x32_bf16 v[22:25], v[240:243], v[208:211], v[22:25]
	v_mfma_f32_16x16x32_bf16 v[18:21], v[232:235], v[216:219], v[18:21]
	v_mfma_f32_16x16x32_bf16 v[14:17], v[240:243], v[216:219], v[14:17]
	v_mfma_f32_16x16x32_bf16 v[10:13], v[232:235], v[224:227], v[10:13]
	v_mfma_f32_16x16x32_bf16 v[6:9], v[240:243], v[224:227], v[6:9]
	v_mfma_f32_16x16x32_bf16 v[34:37], v[236:239], v[204:207], v[34:37]
	v_mfma_f32_16x16x32_bf16 v[30:33], v[244:247], v[204:207], v[30:33]
	v_mfma_f32_16x16x32_bf16 v[26:29], v[236:239], v[212:215], v[26:29]
	v_mfma_f32_16x16x32_bf16 v[22:25], v[244:247], v[212:215], v[22:25]
	v_mfma_f32_16x16x32_bf16 v[18:21], v[236:239], v[220:223], v[18:21]
	v_mfma_f32_16x16x32_bf16 v[14:17], v[244:247], v[220:223], v[14:17]
	v_mfma_f32_16x16x32_bf16 v[10:13], v[236:239], v[228:231], v[10:13]
	v_mfma_f32_16x16x32_bf16 v[6:9], v[244:247], v[228:231], v[6:9]
	s_add_i32 s54, 0, 0x18000
	v_add_u32_e32 v3, s54, v190
	s_barrier
	ds_read_b128 v[154:157], v3
	ds_read_b128 v[158:161], v3 offset:1024
	ds_read_b128 v[162:165], v3 offset:2048
	ds_read_b128 v[166:169], v3 offset:3072
	s_add_u32 s52, s52, 0x80000
	s_addc_u32 s53, s53, 0
	s_mov_b32 m0, s43
	v_lshl_add_u64 v[232:233], s[52:53], 0, v[136:137]
	ds_read_b128 v[170:173], v192 offset:32768
	ds_read_b128 v[204:207], v192 offset:33792
	ds_read_b128 v[208:211], v192 offset:34816
	ds_read_b128 v[212:215], v192 offset:35840
	ds_read_b128 v[216:219], v192 offset:36864
	ds_read_b128 v[220:223], v192 offset:37888
	ds_read_b128 v[224:227], v192 offset:38912
	ds_read_b128 v[228:231], v192 offset:39936
	global_load_lds_dwordx4 v[232:233], off
	v_lshl_add_u64 v[232:233], s[52:53], 0, v[140:141]
	s_mov_b32 m0, s60
	s_nop 0
	global_load_lds_dwordx4 v[232:233], off
	s_waitcnt lgkmcnt(8)
	s_barrier
	s_waitcnt lgkmcnt(0)
	s_waitcnt lgkmcnt(0)
	v_mfma_f32_16x16x32_bf16 v[130:133], v[154:157], v[170:173], v[130:133]
	v_mfma_f32_16x16x32_bf16 v[126:129], v[162:165], v[170:173], v[126:129]
	v_mfma_f32_16x16x32_bf16 v[122:125], v[154:157], v[208:211], v[122:125]
	v_mfma_f32_16x16x32_bf16 v[118:121], v[162:165], v[208:211], v[118:121]
	v_mfma_f32_16x16x32_bf16 v[114:117], v[154:157], v[216:219], v[114:117]
	v_mfma_f32_16x16x32_bf16 v[110:113], v[162:165], v[216:219], v[110:113]
	v_mfma_f32_16x16x32_bf16 v[106:109], v[154:157], v[224:227], v[106:109]
	v_mfma_f32_16x16x32_bf16 v[98:101], v[162:165], v[224:227], v[98:101]
	v_mfma_f32_16x16x32_bf16 v[130:133], v[158:161], v[204:207], v[130:133]
	v_mfma_f32_16x16x32_bf16 v[126:129], v[166:169], v[204:207], v[126:129]
	v_mfma_f32_16x16x32_bf16 v[122:125], v[158:161], v[212:215], v[122:125]
	v_mfma_f32_16x16x32_bf16 v[118:121], v[166:169], v[212:215], v[118:121]
	v_mfma_f32_16x16x32_bf16 v[114:117], v[158:161], v[220:223], v[114:117]
	v_mfma_f32_16x16x32_bf16 v[110:113], v[166:169], v[220:223], v[110:113]
	v_mfma_f32_16x16x32_bf16 v[106:109], v[158:161], v[228:231], v[106:109]
	v_mfma_f32_16x16x32_bf16 v[98:101], v[166:169], v[228:231], v[98:101]
	s_barrier
	s_add_i32 s52, 0, 0x1c000
	s_add_i32 s53, s54, s37
	v_add_u32_e32 v3, s52, v190
	v_lshl_add_u64 v[174:175], v[174:175], 0, s[22:23]
	s_mov_b32 m0, s53
	ds_read_b128 v[232:235], v3
	ds_read_b128 v[236:239], v3 offset:1024
	ds_read_b128 v[240:243], v3 offset:2048
	ds_read_b128 v[244:247], v3 offset:3072
	global_load_lds_dwordx4 v[174:175], off
	v_lshl_add_u64 v[174:175], v[248:249], 0, s[22:23]
	s_add_i32 m0, s53, 0x2000
	s_nop 0
	global_load_lds_dwordx4 v[174:175], off
	s_barrier
	s_waitcnt lgkmcnt(0)
	s_waitcnt lgkmcnt(0)
	v_mfma_f32_16x16x32_bf16 v[102:105], v[232:235], v[170:173], v[102:105]
	v_mfma_f32_16x16x32_bf16 v[94:97], v[240:243], v[170:173], v[94:97]
	v_mfma_f32_16x16x32_bf16 v[90:93], v[232:235], v[208:211], v[90:93]
	v_mfma_f32_16x16x32_bf16 v[86:89], v[240:243], v[208:211], v[86:89]
	v_mfma_f32_16x16x32_bf16 v[82:85], v[232:235], v[216:219], v[82:85]
	v_mfma_f32_16x16x32_bf16 v[78:81], v[240:243], v[216:219], v[78:81]
	v_mfma_f32_16x16x32_bf16 v[74:77], v[232:235], v[224:227], v[74:77]
	v_mfma_f32_16x16x32_bf16 v[70:73], v[240:243], v[224:227], v[70:73]
	v_mfma_f32_16x16x32_bf16 v[102:105], v[236:239], v[204:207], v[102:105]
	v_mfma_f32_16x16x32_bf16 v[94:97], v[244:247], v[204:207], v[94:97]
	v_mfma_f32_16x16x32_bf16 v[90:93], v[236:239], v[212:215], v[90:93]
	v_mfma_f32_16x16x32_bf16 v[86:89], v[244:247], v[212:215], v[86:89]
	v_mfma_f32_16x16x32_bf16 v[82:85], v[236:239], v[220:223], v[82:85]
	v_mfma_f32_16x16x32_bf16 v[78:81], v[244:247], v[220:223], v[78:81]
	v_mfma_f32_16x16x32_bf16 v[74:77], v[236:239], v[228:231], v[74:77]
	v_mfma_f32_16x16x32_bf16 v[70:73], v[244:247], v[228:231], v[70:73]
	s_mov_b32 m0, s63
	v_lshl_add_u64 v[174:175], v[250:251], 0, s[22:23]
	s_barrier
	ds_read_b128 v[170:173], v192 offset:49152
	ds_read_b128 v[204:207], v192 offset:50176
	ds_read_b128 v[208:211], v192 offset:51200
	ds_read_b128 v[212:215], v192 offset:52224
	ds_read_b128 v[216:219], v192 offset:53248
	ds_read_b128 v[220:223], v192 offset:54272
	ds_read_b128 v[224:227], v192 offset:55296
	ds_read_b128 v[228:231], v192 offset:56320
	global_load_lds_dwordx4 v[174:175], off
	v_lshl_add_u64 v[174:175], v[252:253], 0, s[22:23]
	s_mov_b32 m0, s64
	s_nop 0
	global_load_lds_dwordx4 v[174:175], off
	s_barrier
	s_waitcnt lgkmcnt(0)
	s_waitcnt lgkmcnt(0)
	v_mfma_f32_16x16x32_bf16 v[66:69], v[154:157], v[170:173], v[66:69]
	v_mfma_f32_16x16x32_bf16 v[62:65], v[162:165], v[170:173], v[62:65]
	v_mfma_f32_16x16x32_bf16 v[58:61], v[154:157], v[208:211], v[58:61]
	v_mfma_f32_16x16x32_bf16 v[54:57], v[162:165], v[208:211], v[54:57]
	v_mfma_f32_16x16x32_bf16 v[50:53], v[154:157], v[216:219], v[50:53]
	v_mfma_f32_16x16x32_bf16 v[46:49], v[162:165], v[216:219], v[46:49]
	v_mfma_f32_16x16x32_bf16 v[42:45], v[154:157], v[224:227], v[42:45]
	v_mfma_f32_16x16x32_bf16 v[38:41], v[162:165], v[224:227], v[38:41]
	v_mfma_f32_16x16x32_bf16 v[66:69], v[158:161], v[204:207], v[66:69]
	v_mfma_f32_16x16x32_bf16 v[62:65], v[166:169], v[204:207], v[62:65]
	v_mfma_f32_16x16x32_bf16 v[58:61], v[158:161], v[212:215], v[58:61]
	v_mfma_f32_16x16x32_bf16 v[54:57], v[166:169], v[212:215], v[54:57]
	v_mfma_f32_16x16x32_bf16 v[50:53], v[158:161], v[220:223], v[50:53]
	v_mfma_f32_16x16x32_bf16 v[46:49], v[166:169], v[220:223], v[46:49]
	v_mfma_f32_16x16x32_bf16 v[42:45], v[158:161], v[228:231], v[42:45]
	v_mfma_f32_16x16x32_bf16 v[38:41], v[166:169], v[228:231], v[38:41]
	s_barrier
	s_add_i32 s52, s52, s37
	v_lshl_add_u64 v[154:155], v[180:181], 0, s[22:23]
	s_mov_b32 m0, s52
	s_nop 0
	global_load_lds_dwordx4 v[154:155], off
	v_lshl_add_u64 v[154:155], v[184:185], 0, s[22:23]
	s_add_i32 m0, s52, 0x2000
	s_nop 0
	global_load_lds_dwordx4 v[154:155], off
	s_waitcnt vmcnt(6)
	s_barrier
	v_mfma_f32_16x16x32_bf16 v[34:37], v[232:235], v[170:173], v[34:37]
	v_mfma_f32_16x16x32_bf16 v[30:33], v[240:243], v[170:173], v[30:33]
	v_mfma_f32_16x16x32_bf16 v[26:29], v[232:235], v[208:211], v[26:29]
	v_mfma_f32_16x16x32_bf16 v[22:25], v[240:243], v[208:211], v[22:25]
	v_mfma_f32_16x16x32_bf16 v[18:21], v[232:235], v[216:219], v[18:21]
	v_mfma_f32_16x16x32_bf16 v[14:17], v[240:243], v[216:219], v[14:17]
	v_mfma_f32_16x16x32_bf16 v[10:13], v[232:235], v[224:227], v[10:13]
	v_mfma_f32_16x16x32_bf16 v[6:9], v[240:243], v[224:227], v[6:9]
	v_mfma_f32_16x16x32_bf16 v[34:37], v[236:239], v[204:207], v[34:37]
	v_mfma_f32_16x16x32_bf16 v[30:33], v[244:247], v[204:207], v[30:33]
	v_mfma_f32_16x16x32_bf16 v[26:29], v[236:239], v[212:215], v[26:29]
	v_mfma_f32_16x16x32_bf16 v[22:25], v[244:247], v[212:215], v[22:25]
	v_mfma_f32_16x16x32_bf16 v[18:21], v[236:239], v[220:223], v[18:21]
	v_mfma_f32_16x16x32_bf16 v[14:17], v[244:247], v[220:223], v[14:17]
	v_mfma_f32_16x16x32_bf16 v[10:13], v[236:239], v[228:231], v[10:13]
	v_mfma_f32_16x16x32_bf16 v[6:9], v[244:247], v[228:231], v[6:9]
	s_add_u32 s6, s6, 0x100
	s_addc_u32 s7, s7, 0
	s_andn2_b64 s[46:47], s[46:47], exec
	s_and_b64 s[52:53], s[8:9], exec
	s_or_b64 s[46:47], s[46:47], s[52:53]
	s_cmp_ge_i32 s58, s61
	s_barrier
	s_cbranch_scc1 .LBB0_259
	s_mov_b32 s54, s58
	s_branch .LBB0_255

.LBB0_512:
	s_or_b64 exec, exec, s[36:37]
	s_add_i32 s64, s38, 2
	s_add_u32 s36, s16, s6
	v_add_u32_e32 v3, s56, v165
	s_addc_u32 s37, s17, s7
	ds_read_b128 v[170:173], v3
	ds_read_b128 v[174:177], v3 offset:1024
	ds_read_b128 v[178:181], v3 offset:2048
	ds_read_b128 v[182:185], v3 offset:3072
	s_add_u32 s36, s36, 0x100
	s_addc_u32 s37, s37, 0
	s_add_u32 s65, s62, s6
	s_addc_u32 s39, s63, s7
	s_cmp_eq_u32 s54, s38
	s_cselect_b32 s38, s26, s65
	s_cselect_b32 s37, s25, s37
	s_cselect_b32 s36, s61, s36
	s_cselect_b32 s39, s27, s39
	v_lshl_add_u64 v[218:219], v[160:161], 0, s[6:7]
	s_add_i32 m0, s46, 0xc000
	ds_read_b128 v[186:189], v167
	ds_read_b128 v[190:193], v167 offset:1024
	ds_read_b128 v[194:197], v167 offset:2048
	ds_read_b128 v[198:201], v167 offset:3072
	ds_read_b128 v[202:205], v167 offset:4096
	ds_read_b128 v[206:209], v167 offset:5120
	ds_read_b128 v[210:213], v167 offset:6144
	ds_read_b128 v[214:217], v167 offset:7168
	global_load_lds_dwordx4 v[218:219], off
	v_lshl_add_u64 v[218:219], v[162:163], 0, s[6:7]
	s_add_i32 m0, s46, 0xe000
	s_nop 0
	global_load_lds_dwordx4 v[218:219], off
	s_waitcnt lgkmcnt(8)
	s_barrier
	s_waitcnt lgkmcnt(0)
	s_waitcnt lgkmcnt(0)
	v_mfma_f32_16x16x32_bf16 v[130:133], v[170:173], v[186:189], v[130:133]
	v_mfma_f32_16x16x32_bf16 v[126:129], v[178:181], v[186:189], v[126:129]
	v_mfma_f32_16x16x32_bf16 v[122:125], v[170:173], v[194:197], v[122:125]
	v_mfma_f32_16x16x32_bf16 v[118:121], v[178:181], v[194:197], v[118:121]
	v_mfma_f32_16x16x32_bf16 v[114:117], v[170:173], v[202:205], v[114:117]
	v_mfma_f32_16x16x32_bf16 v[110:113], v[178:181], v[202:205], v[110:113]
	v_mfma_f32_16x16x32_bf16 v[106:109], v[170:173], v[210:213], v[106:109]
	v_mfma_f32_16x16x32_bf16 v[98:101], v[178:181], v[210:213], v[98:101]
	v_mfma_f32_16x16x32_bf16 v[130:133], v[174:177], v[190:193], v[130:133]
	v_mfma_f32_16x16x32_bf16 v[126:129], v[182:185], v[190:193], v[126:129]
	v_mfma_f32_16x16x32_bf16 v[122:125], v[174:177], v[198:201], v[122:125]
	v_mfma_f32_16x16x32_bf16 v[118:121], v[182:185], v[198:201], v[118:121]
	v_mfma_f32_16x16x32_bf16 v[114:117], v[174:177], v[206:209], v[114:117]
	v_mfma_f32_16x16x32_bf16 v[110:113], v[182:185], v[206:209], v[110:113]
	v_mfma_f32_16x16x32_bf16 v[106:109], v[174:177], v[214:217], v[106:109]
	v_mfma_f32_16x16x32_bf16 v[98:101], v[182:185], v[214:217], v[98:101]
	s_barrier
	s_add_i32 s65, s56, s45
	v_add_u32_e32 v3, s57, v165
	v_lshl_add_u64 v[234:235], s[38:39], 0, v[138:139]
	s_mov_b32 m0, s65
	ds_read_b128 v[218:221], v3
	ds_read_b128 v[222:225], v3 offset:1024
	ds_read_b128 v[226:229], v3 offset:2048
	ds_read_b128 v[230:233], v3 offset:3072
	global_load_lds_dwordx4 v[234:235], off
	v_lshl_add_u64 v[236:237], s[38:39], 0, v[134:135]
	s_add_i32 m0, s65, 0x2000
	s_nop 0
	global_load_lds_dwordx4 v[236:237], off
	s_barrier
	s_waitcnt lgkmcnt(0)
	s_waitcnt lgkmcnt(0)
	v_mfma_f32_16x16x32_bf16 v[102:105], v[218:221], v[186:189], v[102:105]
	v_mfma_f32_16x16x32_bf16 v[94:97], v[226:229], v[186:189], v[94:97]
	v_mfma_f32_16x16x32_bf16 v[90:93], v[218:221], v[194:197], v[90:93]
	v_mfma_f32_16x16x32_bf16 v[86:89], v[226:229], v[194:197], v[86:89]
	v_mfma_f32_16x16x32_bf16 v[82:85], v[218:221], v[202:205], v[82:85]
	v_mfma_f32_16x16x32_bf16 v[78:81], v[226:229], v[202:205], v[78:81]
	v_mfma_f32_16x16x32_bf16 v[74:77], v[218:221], v[210:213], v[74:77]
	v_mfma_f32_16x16x32_bf16 v[70:73], v[226:229], v[210:213], v[70:73]
	v_mfma_f32_16x16x32_bf16 v[102:105], v[222:225], v[190:193], v[102:105]
	v_mfma_f32_16x16x32_bf16 v[94:97], v[230:233], v[190:193], v[94:97]
	v_mfma_f32_16x16x32_bf16 v[90:93], v[222:225], v[198:201], v[90:93]
	v_mfma_f32_16x16x32_bf16 v[86:89], v[230:233], v[198:201], v[86:89]
	v_mfma_f32_16x16x32_bf16 v[82:85], v[222:225], v[206:209], v[82:85]
	v_mfma_f32_16x16x32_bf16 v[78:81], v[230:233], v[206:209], v[78:81]
	v_mfma_f32_16x16x32_bf16 v[74:77], v[222:225], v[214:217], v[74:77]
	v_mfma_f32_16x16x32_bf16 v[70:73], v[230:233], v[214:217], v[70:73]
	s_mov_b32 m0, s46
	v_lshl_add_u64 v[238:239], s[36:37], 0, v[136:137]
	s_barrier
	ds_read_b128 v[186:189], v167 offset:16384
	ds_read_b128 v[190:193], v167 offset:17408
	ds_read_b128 v[194:197], v167 offset:18432
	ds_read_b128 v[198:201], v167 offset:19456
	ds_read_b128 v[202:205], v167 offset:20480
	ds_read_b128 v[206:209], v167 offset:21504
	ds_read_b128 v[210:213], v167 offset:22528
	ds_read_b128 v[214:217], v167 offset:23552
	global_load_lds_dwordx4 v[238:239], off
	v_lshl_add_u64 v[240:241], s[36:37], 0, v[140:141]
	s_mov_b32 m0, s47
	s_nop 0
	global_load_lds_dwordx4 v[240:241], off
	s_barrier
	s_waitcnt lgkmcnt(0)
	s_waitcnt lgkmcnt(0)
	v_mfma_f32_16x16x32_bf16 v[66:69], v[170:173], v[186:189], v[66:69]
	v_mfma_f32_16x16x32_bf16 v[62:65], v[178:181], v[186:189], v[62:65]
	v_mfma_f32_16x16x32_bf16 v[58:61], v[170:173], v[194:197], v[58:61]
	v_mfma_f32_16x16x32_bf16 v[54:57], v[178:181], v[194:197], v[54:57]
	v_mfma_f32_16x16x32_bf16 v[50:53], v[170:173], v[202:205], v[50:53]
	v_mfma_f32_16x16x32_bf16 v[46:49], v[178:181], v[202:205], v[46:49]
	v_mfma_f32_16x16x32_bf16 v[42:45], v[170:173], v[210:213], v[42:45]
	v_mfma_f32_16x16x32_bf16 v[38:41], v[178:181], v[210:213], v[38:41]
	v_mfma_f32_16x16x32_bf16 v[66:69], v[174:177], v[190:193], v[66:69]
	v_mfma_f32_16x16x32_bf16 v[62:65], v[182:185], v[190:193], v[62:65]
	v_mfma_f32_16x16x32_bf16 v[58:61], v[174:177], v[198:201], v[58:61]
	v_mfma_f32_16x16x32_bf16 v[54:57], v[182:185], v[198:201], v[54:57]
	v_mfma_f32_16x16x32_bf16 v[50:53], v[174:177], v[206:209], v[50:53]
	v_mfma_f32_16x16x32_bf16 v[46:49], v[182:185], v[206:209], v[46:49]
	v_mfma_f32_16x16x32_bf16 v[42:45], v[174:177], v[214:217], v[42:45]
	v_mfma_f32_16x16x32_bf16 v[38:41], v[182:185], v[214:217], v[38:41]
	s_barrier
	s_add_u32 s38, s38, s10
	s_addc_u32 s39, s39, s11
	s_add_i32 s65, s57, s45
	v_lshl_add_u64 v[242:243], s[38:39], 0, v[138:139]
	s_mov_b32 m0, s65
	v_lshl_add_u64 v[244:245], s[38:39], 0, v[134:135]
	global_load_lds_dwordx4 v[242:243], off
	s_add_i32 m0, s65, 0x2000
	s_nop 0
	global_load_lds_dwordx4 v[244:245], off
	s_waitcnt vmcnt(6)
	s_barrier
	v_mfma_f32_16x16x32_bf16 v[34:37], v[218:221], v[186:189], v[34:37]
	v_mfma_f32_16x16x32_bf16 v[30:33], v[226:229], v[186:189], v[30:33]
	v_mfma_f32_16x16x32_bf16 v[26:29], v[218:221], v[194:197], v[26:29]
	v_mfma_f32_16x16x32_bf16 v[22:25], v[226:229], v[194:197], v[22:25]
	v_mfma_f32_16x16x32_bf16 v[18:21], v[218:221], v[202:205], v[18:21]
	v_mfma_f32_16x16x32_bf16 v[14:17], v[226:229], v[202:205], v[14:17]
	v_mfma_f32_16x16x32_bf16 v[10:13], v[218:221], v[210:213], v[10:13]
	v_mfma_f32_16x16x32_bf16 v[6:9], v[226:229], v[210:213], v[6:9]
	v_mfma_f32_16x16x32_bf16 v[34:37], v[222:225], v[190:193], v[34:37]
	v_mfma_f32_16x16x32_bf16 v[30:33], v[230:233], v[190:193], v[30:33]
	v_mfma_f32_16x16x32_bf16 v[26:29], v[222:225], v[198:201], v[26:29]
	v_mfma_f32_16x16x32_bf16 v[22:25], v[230:233], v[198:201], v[22:25]
	v_mfma_f32_16x16x32_bf16 v[18:21], v[222:225], v[206:209], v[18:21]
	v_mfma_f32_16x16x32_bf16 v[14:17], v[230:233], v[206:209], v[14:17]
	v_mfma_f32_16x16x32_bf16 v[10:13], v[222:225], v[214:217], v[10:13]
	v_mfma_f32_16x16x32_bf16 v[6:9], v[230:233], v[214:217], v[6:9]
	s_add_i32 s38, 0, 0x18000
	v_add_u32_e32 v3, s38, v165
	s_barrier
	ds_read_b128 v[170:173], v3
	ds_read_b128 v[174:177], v3 offset:1024
	ds_read_b128 v[178:181], v3 offset:2048
	ds_read_b128 v[182:185], v3 offset:3072
	s_add_u32 s36, s36, 0x10000
	s_addc_u32 s37, s37, 0
	s_mov_b32 m0, s48
	v_lshl_add_u64 v[218:219], s[36:37], 0, v[136:137]
	ds_read_b128 v[186:189], v167 offset:32768
	ds_read_b128 v[190:193], v167 offset:33792
	ds_read_b128 v[194:197], v167 offset:34816
	ds_read_b128 v[198:201], v167 offset:35840
	ds_read_b128 v[202:205], v167 offset:36864
	ds_read_b128 v[206:209], v167 offset:37888
	ds_read_b128 v[210:213], v167 offset:38912
	ds_read_b128 v[214:217], v167 offset:39936
	global_load_lds_dwordx4 v[218:219], off
	v_lshl_add_u64 v[218:219], s[36:37], 0, v[140:141]
	s_mov_b32 m0, s49
	s_nop 0
	global_load_lds_dwordx4 v[218:219], off
	s_waitcnt lgkmcnt(8)
	s_barrier
	s_waitcnt lgkmcnt(0)
	s_waitcnt lgkmcnt(0)
	v_mfma_f32_16x16x32_bf16 v[130:133], v[170:173], v[186:189], v[130:133]
	v_mfma_f32_16x16x32_bf16 v[126:129], v[178:181], v[186:189], v[126:129]
	v_mfma_f32_16x16x32_bf16 v[122:125], v[170:173], v[194:197], v[122:125]
	v_mfma_f32_16x16x32_bf16 v[118:121], v[178:181], v[194:197], v[118:121]
	v_mfma_f32_16x16x32_bf16 v[114:117], v[170:173], v[202:205], v[114:117]
	v_mfma_f32_16x16x32_bf16 v[110:113], v[178:181], v[202:205], v[110:113]
	v_mfma_f32_16x16x32_bf16 v[106:109], v[170:173], v[210:213], v[106:109]
	v_mfma_f32_16x16x32_bf16 v[98:101], v[178:181], v[210:213], v[98:101]
	v_mfma_f32_16x16x32_bf16 v[130:133], v[174:177], v[190:193], v[130:133]
	v_mfma_f32_16x16x32_bf16 v[126:129], v[182:185], v[190:193], v[126:129]
	v_mfma_f32_16x16x32_bf16 v[122:125], v[174:177], v[198:201], v[122:125]
	v_mfma_f32_16x16x32_bf16 v[118:121], v[182:185], v[198:201], v[118:121]
	v_mfma_f32_16x16x32_bf16 v[114:117], v[174:177], v[206:209], v[114:117]
	v_mfma_f32_16x16x32_bf16 v[110:113], v[182:185], v[206:209], v[110:113]
	v_mfma_f32_16x16x32_bf16 v[106:109], v[174:177], v[214:217], v[106:109]
	v_mfma_f32_16x16x32_bf16 v[98:101], v[182:185], v[214:217], v[98:101]
	s_barrier
	s_add_i32 s36, 0, 0x1c000
	s_add_i32 s37, s38, s45
	v_add_u32_e32 v3, s36, v165
	v_lshl_add_u64 v[234:235], v[234:235], 0, s[20:21]
	s_mov_b32 m0, s37
	ds_read_b128 v[218:221], v3
	ds_read_b128 v[222:225], v3 offset:1024
	ds_read_b128 v[226:229], v3 offset:2048
	ds_read_b128 v[230:233], v3 offset:3072
	global_load_lds_dwordx4 v[234:235], off
	v_lshl_add_u64 v[234:235], v[236:237], 0, s[20:21]
	s_add_i32 m0, s37, 0x2000
	s_nop 0
	global_load_lds_dwordx4 v[234:235], off
	s_barrier
	s_waitcnt lgkmcnt(0)
	s_waitcnt lgkmcnt(0)
	v_mfma_f32_16x16x32_bf16 v[102:105], v[218:221], v[186:189], v[102:105]
	v_mfma_f32_16x16x32_bf16 v[94:97], v[226:229], v[186:189], v[94:97]
	v_mfma_f32_16x16x32_bf16 v[90:93], v[218:221], v[194:197], v[90:93]
	v_mfma_f32_16x16x32_bf16 v[86:89], v[226:229], v[194:197], v[86:89]
	v_mfma_f32_16x16x32_bf16 v[82:85], v[218:221], v[202:205], v[82:85]
	v_mfma_f32_16x16x32_bf16 v[78:81], v[226:229], v[202:205], v[78:81]
	v_mfma_f32_16x16x32_bf16 v[74:77], v[218:221], v[210:213], v[74:77]
	v_mfma_f32_16x16x32_bf16 v[70:73], v[226:229], v[210:213], v[70:73]
	v_mfma_f32_16x16x32_bf16 v[102:105], v[222:225], v[190:193], v[102:105]
	v_mfma_f32_16x16x32_bf16 v[94:97], v[230:233], v[190:193], v[94:97]
	v_mfma_f32_16x16x32_bf16 v[90:93], v[222:225], v[198:201], v[90:93]
	v_mfma_f32_16x16x32_bf16 v[86:89], v[230:233], v[198:201], v[86:89]
	v_mfma_f32_16x16x32_bf16 v[82:85], v[222:225], v[206:209], v[82:85]
	v_mfma_f32_16x16x32_bf16 v[78:81], v[230:233], v[206:209], v[78:81]
	v_mfma_f32_16x16x32_bf16 v[74:77], v[222:225], v[214:217], v[74:77]
	v_mfma_f32_16x16x32_bf16 v[70:73], v[230:233], v[214:217], v[70:73]
	s_mov_b32 m0, s51
	v_lshl_add_u64 v[234:235], v[238:239], 0, s[20:21]
	s_barrier
	ds_read_b128 v[186:189], v167 offset:49152
	ds_read_b128 v[190:193], v167 offset:50176
	ds_read_b128 v[194:197], v167 offset:51200
	ds_read_b128 v[198:201], v167 offset:52224
	ds_read_b128 v[202:205], v167 offset:53248
	ds_read_b128 v[206:209], v167 offset:54272
	ds_read_b128 v[210:213], v167 offset:55296
	ds_read_b128 v[214:217], v167 offset:56320
	global_load_lds_dwordx4 v[234:235], off
	v_lshl_add_u64 v[234:235], v[240:241], 0, s[20:21]
	s_mov_b32 m0, s52
	s_nop 0
	global_load_lds_dwordx4 v[234:235], off
	s_barrier
	s_waitcnt lgkmcnt(0)
	s_waitcnt lgkmcnt(0)
	v_mfma_f32_16x16x32_bf16 v[66:69], v[170:173], v[186:189], v[66:69]
	v_mfma_f32_16x16x32_bf16 v[62:65], v[178:181], v[186:189], v[62:65]
	v_mfma_f32_16x16x32_bf16 v[58:61], v[170:173], v[194:197], v[58:61]
	v_mfma_f32_16x16x32_bf16 v[54:57], v[178:181], v[194:197], v[54:57]
	v_mfma_f32_16x16x32_bf16 v[50:53], v[170:173], v[202:205], v[50:53]
	v_mfma_f32_16x16x32_bf16 v[46:49], v[178:181], v[202:205], v[46:49]
	v_mfma_f32_16x16x32_bf16 v[42:45], v[170:173], v[210:213], v[42:45]
	v_mfma_f32_16x16x32_bf16 v[38:41], v[178:181], v[210:213], v[38:41]
	v_mfma_f32_16x16x32_bf16 v[66:69], v[174:177], v[190:193], v[66:69]
	v_mfma_f32_16x16x32_bf16 v[62:65], v[182:185], v[190:193], v[62:65]
	v_mfma_f32_16x16x32_bf16 v[58:61], v[174:177], v[198:201], v[58:61]
	v_mfma_f32_16x16x32_bf16 v[54:57], v[182:185], v[198:201], v[54:57]
	v_mfma_f32_16x16x32_bf16 v[50:53], v[174:177], v[206:209], v[50:53]
	v_mfma_f32_16x16x32_bf16 v[46:49], v[182:185], v[206:209], v[46:49]
	v_mfma_f32_16x16x32_bf16 v[42:45], v[174:177], v[214:217], v[42:45]
	v_mfma_f32_16x16x32_bf16 v[38:41], v[182:185], v[214:217], v[38:41]
	s_barrier
	s_add_i32 s36, s36, s45
	v_lshl_add_u64 v[170:171], v[242:243], 0, s[20:21]
	s_mov_b32 m0, s36
	s_nop 0
	global_load_lds_dwordx4 v[170:171], off
	v_lshl_add_u64 v[170:171], v[244:245], 0, s[20:21]
	s_add_i32 m0, s36, 0x2000
	s_nop 0
	global_load_lds_dwordx4 v[170:171], off
	s_waitcnt vmcnt(6)
	s_barrier
	v_mfma_f32_16x16x32_bf16 v[34:37], v[218:221], v[186:189], v[34:37]
	v_mfma_f32_16x16x32_bf16 v[30:33], v[226:229], v[186:189], v[30:33]
	v_mfma_f32_16x16x32_bf16 v[26:29], v[218:221], v[194:197], v[26:29]
	v_mfma_f32_16x16x32_bf16 v[22:25], v[226:229], v[194:197], v[22:25]
	v_mfma_f32_16x16x32_bf16 v[18:21], v[218:221], v[202:205], v[18:21]
	v_mfma_f32_16x16x32_bf16 v[14:17], v[226:229], v[202:205], v[14:17]
	v_mfma_f32_16x16x32_bf16 v[10:13], v[218:221], v[210:213], v[10:13]
	v_mfma_f32_16x16x32_bf16 v[6:9], v[226:229], v[210:213], v[6:9]
	v_mfma_f32_16x16x32_bf16 v[34:37], v[222:225], v[190:193], v[34:37]
	v_mfma_f32_16x16x32_bf16 v[30:33], v[230:233], v[190:193], v[30:33]
	v_mfma_f32_16x16x32_bf16 v[26:29], v[222:225], v[198:201], v[26:29]
	v_mfma_f32_16x16x32_bf16 v[22:25], v[230:233], v[198:201], v[22:25]
	v_mfma_f32_16x16x32_bf16 v[18:21], v[222:225], v[206:209], v[18:21]
	v_mfma_f32_16x16x32_bf16 v[14:17], v[230:233], v[206:209], v[14:17]
	v_mfma_f32_16x16x32_bf16 v[10:13], v[222:225], v[214:217], v[10:13]
	v_mfma_f32_16x16x32_bf16 v[6:9], v[230:233], v[214:217], v[6:9]
	s_add_u32 s6, s6, 0x100
	s_addc_u32 s7, s7, 0
	s_andn2_b64 s[30:31], s[30:31], exec
	s_and_b64 s[36:37], s[34:35], exec
	s_or_b64 s[30:31], s[30:31], s[36:37]
	s_cmp_ge_i32 s64, s50
	s_mov_b32 s38, s64
	s_barrier
	s_cbranch_scc1 .LBB0_515

.LBB0_874:
	s_or_b64 exec, exec, s[34:35]
	s_add_i32 s62, s36, 2
	s_add_u32 s34, s14, s6
	v_add_u32_e32 v3, s55, v198
	s_addc_u32 s35, s15, s7
	ds_read_b128 v[168:171], v3
	ds_read_b128 v[172:175], v3 offset:1024
	ds_read_b128 v[176:179], v3 offset:2048
	ds_read_b128 v[180:183], v3 offset:3072
	s_add_u32 s34, s34, 0x100
	s_addc_u32 s35, s35, 0
	s_add_u32 s63, s60, s6
	s_addc_u32 s37, s61, s7
	s_cmp_eq_u32 s54, s36
	s_cselect_b32 s36, s24, s63
	s_cselect_b32 s35, s23, s35
	s_cselect_b32 s34, s33, s34
	s_cselect_b32 s37, s25, s37
	v_lshl_add_u64 v[140:141], v[136:137], 0, s[6:7]
	s_add_i32 m0, s45, 0xc000
	ds_read_b128 v[184:187], v200
	ds_read_b128 v[188:191], v200 offset:1024
	ds_read_b128 v[192:195], v200 offset:2048
	ds_read_b128 v[202:205], v200 offset:3072
	ds_read_b128 v[206:209], v200 offset:4096
	ds_read_b128 v[210:213], v200 offset:5120
	ds_read_b128 v[214:217], v200 offset:6144
	ds_read_b128 v[218:221], v200 offset:7168
	global_load_lds_dwordx4 v[140:141], off
	v_lshl_add_u64 v[140:141], v[138:139], 0, s[6:7]
	s_add_i32 m0, s45, 0xe000
	s_nop 0
	global_load_lds_dwordx4 v[140:141], off
	s_waitcnt lgkmcnt(8)
	s_barrier
	s_waitcnt lgkmcnt(0)
	s_waitcnt lgkmcnt(0)
	v_mfma_f32_16x16x32_bf16 v[130:133], v[168:171], v[184:187], v[130:133]
	v_mfma_f32_16x16x32_bf16 v[126:129], v[176:179], v[184:187], v[126:129]
	v_mfma_f32_16x16x32_bf16 v[122:125], v[168:171], v[192:195], v[122:125]
	v_mfma_f32_16x16x32_bf16 v[118:121], v[176:179], v[192:195], v[118:121]
	v_mfma_f32_16x16x32_bf16 v[114:117], v[168:171], v[206:209], v[114:117]
	v_mfma_f32_16x16x32_bf16 v[110:113], v[176:179], v[206:209], v[110:113]
	v_mfma_f32_16x16x32_bf16 v[106:109], v[168:171], v[214:217], v[106:109]
	v_mfma_f32_16x16x32_bf16 v[98:101], v[176:179], v[214:217], v[98:101]
	v_mfma_f32_16x16x32_bf16 v[130:133], v[172:175], v[188:191], v[130:133]
	v_mfma_f32_16x16x32_bf16 v[126:129], v[180:183], v[188:191], v[126:129]
	v_mfma_f32_16x16x32_bf16 v[122:125], v[172:175], v[202:205], v[122:125]
	v_mfma_f32_16x16x32_bf16 v[118:121], v[180:183], v[202:205], v[118:121]
	v_mfma_f32_16x16x32_bf16 v[114:117], v[172:175], v[210:213], v[114:117]
	v_mfma_f32_16x16x32_bf16 v[110:113], v[180:183], v[210:213], v[110:113]
	v_mfma_f32_16x16x32_bf16 v[106:109], v[172:175], v[218:221], v[106:109]
	v_mfma_f32_16x16x32_bf16 v[98:101], v[180:183], v[218:221], v[98:101]
	s_barrier
	s_add_i32 s63, s55, s44
	v_add_u32_e32 v3, s56, v198
	v_lshl_add_u64 v[140:141], s[36:37], 0, v[148:149]
	s_mov_b32 m0, s63
	ds_read_b128 v[222:225], v3
	ds_read_b128 v[226:229], v3 offset:1024
	ds_read_b128 v[230:233], v3 offset:2048
	ds_read_b128 v[234:237], v3 offset:3072
	global_load_lds_dwordx4 v[140:141], off
	v_lshl_add_u64 v[144:145], s[36:37], 0, v[152:153]
	s_add_i32 m0, s63, 0x2000
	s_nop 0
	global_load_lds_dwordx4 v[144:145], off
	s_barrier
	s_waitcnt lgkmcnt(0)
	s_waitcnt lgkmcnt(0)
	v_mfma_f32_16x16x32_bf16 v[102:105], v[222:225], v[184:187], v[102:105]
	v_mfma_f32_16x16x32_bf16 v[94:97], v[230:233], v[184:187], v[94:97]
	v_mfma_f32_16x16x32_bf16 v[90:93], v[222:225], v[192:195], v[90:93]
	v_mfma_f32_16x16x32_bf16 v[86:89], v[230:233], v[192:195], v[86:89]
	v_mfma_f32_16x16x32_bf16 v[82:85], v[222:225], v[206:209], v[82:85]
	v_mfma_f32_16x16x32_bf16 v[78:81], v[230:233], v[206:209], v[78:81]
	v_mfma_f32_16x16x32_bf16 v[74:77], v[222:225], v[214:217], v[74:77]
	v_mfma_f32_16x16x32_bf16 v[70:73], v[230:233], v[214:217], v[70:73]
	v_mfma_f32_16x16x32_bf16 v[102:105], v[226:229], v[188:191], v[102:105]
	v_mfma_f32_16x16x32_bf16 v[94:97], v[234:237], v[188:191], v[94:97]
	v_mfma_f32_16x16x32_bf16 v[90:93], v[226:229], v[202:205], v[90:93]
	v_mfma_f32_16x16x32_bf16 v[86:89], v[234:237], v[202:205], v[86:89]
	v_mfma_f32_16x16x32_bf16 v[82:85], v[226:229], v[210:213], v[82:85]
	v_mfma_f32_16x16x32_bf16 v[78:81], v[234:237], v[210:213], v[78:81]
	v_mfma_f32_16x16x32_bf16 v[74:77], v[226:229], v[218:221], v[74:77]
	v_mfma_f32_16x16x32_bf16 v[70:73], v[234:237], v[218:221], v[70:73]
	s_mov_b32 m0, s45
	v_lshl_add_u64 v[196:197], s[34:35], 0, v[146:147]
	s_barrier
	ds_read_b128 v[184:187], v200 offset:16384
	ds_read_b128 v[188:191], v200 offset:17408
	ds_read_b128 v[192:195], v200 offset:18432
	ds_read_b128 v[202:205], v200 offset:19456
	ds_read_b128 v[206:209], v200 offset:20480
	ds_read_b128 v[210:213], v200 offset:21504
	ds_read_b128 v[214:217], v200 offset:22528
	ds_read_b128 v[218:221], v200 offset:23552
	global_load_lds_dwordx4 v[196:197], off
	v_lshl_add_u64 v[238:239], s[34:35], 0, v[150:151]
	s_mov_b32 m0, s46
	s_nop 0
	global_load_lds_dwordx4 v[238:239], off
	s_barrier
	s_waitcnt lgkmcnt(0)
	s_waitcnt lgkmcnt(0)
	v_mfma_f32_16x16x32_bf16 v[66:69], v[168:171], v[184:187], v[66:69]
	v_mfma_f32_16x16x32_bf16 v[62:65], v[176:179], v[184:187], v[62:65]
	v_mfma_f32_16x16x32_bf16 v[58:61], v[168:171], v[192:195], v[58:61]
	v_mfma_f32_16x16x32_bf16 v[54:57], v[176:179], v[192:195], v[54:57]
	v_mfma_f32_16x16x32_bf16 v[50:53], v[168:171], v[206:209], v[50:53]
	v_mfma_f32_16x16x32_bf16 v[46:49], v[176:179], v[206:209], v[46:49]
	v_mfma_f32_16x16x32_bf16 v[42:45], v[168:171], v[214:217], v[42:45]
	v_mfma_f32_16x16x32_bf16 v[38:41], v[176:179], v[214:217], v[38:41]
	v_mfma_f32_16x16x32_bf16 v[66:69], v[172:175], v[188:191], v[66:69]
	v_mfma_f32_16x16x32_bf16 v[62:65], v[180:183], v[188:191], v[62:65]
	v_mfma_f32_16x16x32_bf16 v[58:61], v[172:175], v[202:205], v[58:61]
	v_mfma_f32_16x16x32_bf16 v[54:57], v[180:183], v[202:205], v[54:57]
	v_mfma_f32_16x16x32_bf16 v[50:53], v[172:175], v[210:213], v[50:53]
	v_mfma_f32_16x16x32_bf16 v[46:49], v[180:183], v[210:213], v[46:49]
	v_mfma_f32_16x16x32_bf16 v[42:45], v[172:175], v[218:221], v[42:45]
	v_mfma_f32_16x16x32_bf16 v[38:41], v[180:183], v[218:221], v[38:41]
	s_barrier
	s_add_u32 s36, s36, s8
	s_addc_u32 s37, s37, s9
	s_add_i32 s63, s56, s44
	v_lshl_add_u64 v[240:241], s[36:37], 0, v[148:149]
	s_mov_b32 m0, s63
	v_lshl_add_u64 v[242:243], s[36:37], 0, v[152:153]
	global_load_lds_dwordx4 v[240:241], off
	s_add_i32 m0, s63, 0x2000
	s_nop 0
	global_load_lds_dwordx4 v[242:243], off
	s_waitcnt vmcnt(6)
	s_barrier
	v_mfma_f32_16x16x32_bf16 v[34:37], v[222:225], v[184:187], v[34:37]
	v_mfma_f32_16x16x32_bf16 v[30:33], v[230:233], v[184:187], v[30:33]
	v_mfma_f32_16x16x32_bf16 v[26:29], v[222:225], v[192:195], v[26:29]
	v_mfma_f32_16x16x32_bf16 v[22:25], v[230:233], v[192:195], v[22:25]
	v_mfma_f32_16x16x32_bf16 v[18:21], v[222:225], v[206:209], v[18:21]
	v_mfma_f32_16x16x32_bf16 v[14:17], v[230:233], v[206:209], v[14:17]
	v_mfma_f32_16x16x32_bf16 v[10:13], v[222:225], v[214:217], v[10:13]
	v_mfma_f32_16x16x32_bf16 v[6:9], v[230:233], v[214:217], v[6:9]
	v_mfma_f32_16x16x32_bf16 v[34:37], v[226:229], v[188:191], v[34:37]
	v_mfma_f32_16x16x32_bf16 v[30:33], v[234:237], v[188:191], v[30:33]
	v_mfma_f32_16x16x32_bf16 v[26:29], v[226:229], v[202:205], v[26:29]
	v_mfma_f32_16x16x32_bf16 v[22:25], v[234:237], v[202:205], v[22:25]
	v_mfma_f32_16x16x32_bf16 v[18:21], v[226:229], v[210:213], v[18:21]
	v_mfma_f32_16x16x32_bf16 v[14:17], v[234:237], v[210:213], v[14:17]
	v_mfma_f32_16x16x32_bf16 v[10:13], v[226:229], v[218:221], v[10:13]
	v_mfma_f32_16x16x32_bf16 v[6:9], v[234:237], v[218:221], v[6:9]
	s_add_i32 s36, 0, 0x18000
	v_add_u32_e32 v3, s36, v198
	s_barrier
	ds_read_b128 v[168:171], v3
	ds_read_b128 v[172:175], v3 offset:1024
	ds_read_b128 v[176:179], v3 offset:2048
	ds_read_b128 v[180:183], v3 offset:3072
	s_add_u32 s34, s34, 0x80000
	s_addc_u32 s35, s35, 0
	s_mov_b32 m0, s47
	v_lshl_add_u64 v[222:223], s[34:35], 0, v[146:147]
	ds_read_b128 v[184:187], v200 offset:32768
	ds_read_b128 v[188:191], v200 offset:33792
	ds_read_b128 v[192:195], v200 offset:34816
	ds_read_b128 v[202:205], v200 offset:35840
	ds_read_b128 v[206:209], v200 offset:36864
	ds_read_b128 v[210:213], v200 offset:37888
	ds_read_b128 v[214:217], v200 offset:38912
	ds_read_b128 v[218:221], v200 offset:39936
	global_load_lds_dwordx4 v[222:223], off
	v_lshl_add_u64 v[222:223], s[34:35], 0, v[150:151]
	s_mov_b32 m0, s48
	s_nop 0
	global_load_lds_dwordx4 v[222:223], off
	s_waitcnt lgkmcnt(8)
	s_barrier
	s_waitcnt lgkmcnt(0)
	s_waitcnt lgkmcnt(0)
	v_mfma_f32_16x16x32_bf16 v[130:133], v[168:171], v[184:187], v[130:133]
	v_mfma_f32_16x16x32_bf16 v[126:129], v[176:179], v[184:187], v[126:129]
	v_mfma_f32_16x16x32_bf16 v[122:125], v[168:171], v[192:195], v[122:125]
	v_mfma_f32_16x16x32_bf16 v[118:121], v[176:179], v[192:195], v[118:121]
	v_mfma_f32_16x16x32_bf16 v[114:117], v[168:171], v[206:209], v[114:117]
	v_mfma_f32_16x16x32_bf16 v[110:113], v[176:179], v[206:209], v[110:113]
	v_mfma_f32_16x16x32_bf16 v[106:109], v[168:171], v[214:217], v[106:109]
	v_mfma_f32_16x16x32_bf16 v[98:101], v[176:179], v[214:217], v[98:101]
	v_mfma_f32_16x16x32_bf16 v[130:133], v[172:175], v[188:191], v[130:133]
	v_mfma_f32_16x16x32_bf16 v[126:129], v[180:183], v[188:191], v[126:129]
	v_mfma_f32_16x16x32_bf16 v[122:125], v[172:175], v[202:205], v[122:125]
	v_mfma_f32_16x16x32_bf16 v[118:121], v[180:183], v[202:205], v[118:121]
	v_mfma_f32_16x16x32_bf16 v[114:117], v[172:175], v[210:213], v[114:117]
	v_mfma_f32_16x16x32_bf16 v[110:113], v[180:183], v[210:213], v[110:113]
	v_mfma_f32_16x16x32_bf16 v[106:109], v[172:175], v[218:221], v[106:109]
	v_mfma_f32_16x16x32_bf16 v[98:101], v[180:183], v[218:221], v[98:101]
	s_barrier
	s_add_i32 s34, 0, 0x1c000
	s_add_i32 s35, s36, s44
	v_add_u32_e32 v3, s34, v198
	v_lshl_add_u64 v[140:141], v[140:141], 0, s[18:19]
	s_mov_b32 m0, s35
	ds_read_b128 v[222:225], v3
	ds_read_b128 v[226:229], v3 offset:1024
	ds_read_b128 v[230:233], v3 offset:2048
	ds_read_b128 v[234:237], v3 offset:3072
	global_load_lds_dwordx4 v[140:141], off
	v_lshl_add_u64 v[140:141], v[144:145], 0, s[18:19]
	s_add_i32 m0, s35, 0x2000
	s_nop 0
	global_load_lds_dwordx4 v[140:141], off
	s_barrier
	s_waitcnt lgkmcnt(0)
	s_waitcnt lgkmcnt(0)
	v_mfma_f32_16x16x32_bf16 v[102:105], v[222:225], v[184:187], v[102:105]
	v_mfma_f32_16x16x32_bf16 v[94:97], v[230:233], v[184:187], v[94:97]
	v_mfma_f32_16x16x32_bf16 v[90:93], v[222:225], v[192:195], v[90:93]
	v_mfma_f32_16x16x32_bf16 v[86:89], v[230:233], v[192:195], v[86:89]
	v_mfma_f32_16x16x32_bf16 v[82:85], v[222:225], v[206:209], v[82:85]
	v_mfma_f32_16x16x32_bf16 v[78:81], v[230:233], v[206:209], v[78:81]
	v_mfma_f32_16x16x32_bf16 v[74:77], v[222:225], v[214:217], v[74:77]
	v_mfma_f32_16x16x32_bf16 v[70:73], v[230:233], v[214:217], v[70:73]
	v_mfma_f32_16x16x32_bf16 v[102:105], v[226:229], v[188:191], v[102:105]
	v_mfma_f32_16x16x32_bf16 v[94:97], v[234:237], v[188:191], v[94:97]
	v_mfma_f32_16x16x32_bf16 v[90:93], v[226:229], v[202:205], v[90:93]
	v_mfma_f32_16x16x32_bf16 v[86:89], v[234:237], v[202:205], v[86:89]
	v_mfma_f32_16x16x32_bf16 v[82:85], v[226:229], v[210:213], v[82:85]
	v_mfma_f32_16x16x32_bf16 v[78:81], v[234:237], v[210:213], v[78:81]
	v_mfma_f32_16x16x32_bf16 v[74:77], v[226:229], v[218:221], v[74:77]
	v_mfma_f32_16x16x32_bf16 v[70:73], v[234:237], v[218:221], v[70:73]
	s_mov_b32 m0, s52
	v_lshl_add_u64 v[140:141], v[196:197], 0, s[18:19]
	s_barrier
	ds_read_b128 v[184:187], v200 offset:49152
	ds_read_b128 v[188:191], v200 offset:50176
	ds_read_b128 v[192:195], v200 offset:51200
	ds_read_b128 v[202:205], v200 offset:52224
	ds_read_b128 v[206:209], v200 offset:53248
	ds_read_b128 v[210:213], v200 offset:54272
	ds_read_b128 v[214:217], v200 offset:55296
	ds_read_b128 v[218:221], v200 offset:56320
	global_load_lds_dwordx4 v[140:141], off
	v_lshl_add_u64 v[140:141], v[238:239], 0, s[18:19]
	s_mov_b32 m0, s53
	s_nop 0
	global_load_lds_dwordx4 v[140:141], off
	s_barrier
	s_waitcnt lgkmcnt(0)
	s_waitcnt lgkmcnt(0)
	v_mfma_f32_16x16x32_bf16 v[66:69], v[168:171], v[184:187], v[66:69]
	v_mfma_f32_16x16x32_bf16 v[62:65], v[176:179], v[184:187], v[62:65]
	v_mfma_f32_16x16x32_bf16 v[58:61], v[168:171], v[192:195], v[58:61]
	v_mfma_f32_16x16x32_bf16 v[54:57], v[176:179], v[192:195], v[54:57]
	v_mfma_f32_16x16x32_bf16 v[50:53], v[168:171], v[206:209], v[50:53]
	v_mfma_f32_16x16x32_bf16 v[46:49], v[176:179], v[206:209], v[46:49]
	v_mfma_f32_16x16x32_bf16 v[42:45], v[168:171], v[214:217], v[42:45]
	v_mfma_f32_16x16x32_bf16 v[38:41], v[176:179], v[214:217], v[38:41]
	v_mfma_f32_16x16x32_bf16 v[66:69], v[172:175], v[188:191], v[66:69]
	v_mfma_f32_16x16x32_bf16 v[62:65], v[180:183], v[188:191], v[62:65]
	v_mfma_f32_16x16x32_bf16 v[58:61], v[172:175], v[202:205], v[58:61]
	v_mfma_f32_16x16x32_bf16 v[54:57], v[180:183], v[202:205], v[54:57]
	v_mfma_f32_16x16x32_bf16 v[50:53], v[172:175], v[210:213], v[50:53]
	v_mfma_f32_16x16x32_bf16 v[46:49], v[180:183], v[210:213], v[46:49]
	v_mfma_f32_16x16x32_bf16 v[42:45], v[172:175], v[218:221], v[42:45]
	v_mfma_f32_16x16x32_bf16 v[38:41], v[180:183], v[218:221], v[38:41]
	s_barrier
	s_add_i32 s34, s34, s44
	v_lshl_add_u64 v[140:141], v[240:241], 0, s[18:19]
	s_mov_b32 m0, s34
	s_nop 0
	global_load_lds_dwordx4 v[140:141], off
	v_lshl_add_u64 v[140:141], v[242:243], 0, s[18:19]
	s_add_i32 m0, s34, 0x2000
	s_nop 0
	global_load_lds_dwordx4 v[140:141], off
	s_waitcnt vmcnt(6)
	s_barrier
	v_mfma_f32_16x16x32_bf16 v[34:37], v[222:225], v[184:187], v[34:37]
	v_mfma_f32_16x16x32_bf16 v[30:33], v[230:233], v[184:187], v[30:33]
	v_mfma_f32_16x16x32_bf16 v[26:29], v[222:225], v[192:195], v[26:29]
	v_mfma_f32_16x16x32_bf16 v[22:25], v[230:233], v[192:195], v[22:25]
	v_mfma_f32_16x16x32_bf16 v[18:21], v[222:225], v[206:209], v[18:21]
	v_mfma_f32_16x16x32_bf16 v[14:17], v[230:233], v[206:209], v[14:17]
	v_mfma_f32_16x16x32_bf16 v[10:13], v[222:225], v[214:217], v[10:13]
	v_mfma_f32_16x16x32_bf16 v[6:9], v[230:233], v[214:217], v[6:9]
	v_mfma_f32_16x16x32_bf16 v[34:37], v[226:229], v[188:191], v[34:37]
	v_mfma_f32_16x16x32_bf16 v[30:33], v[234:237], v[188:191], v[30:33]
	v_mfma_f32_16x16x32_bf16 v[26:29], v[226:229], v[202:205], v[26:29]
	v_mfma_f32_16x16x32_bf16 v[22:25], v[234:237], v[202:205], v[22:25]
	v_mfma_f32_16x16x32_bf16 v[18:21], v[226:229], v[210:213], v[18:21]
	v_mfma_f32_16x16x32_bf16 v[14:17], v[234:237], v[210:213], v[14:17]
	v_mfma_f32_16x16x32_bf16 v[10:13], v[226:229], v[218:221], v[10:13]
	v_mfma_f32_16x16x32_bf16 v[6:9], v[234:237], v[218:221], v[6:9]
	s_add_u32 s6, s6, 0x100
	s_addc_u32 s7, s7, 0
	s_andn2_b64 s[28:29], s[28:29], exec
	s_and_b64 s[34:35], s[30:31], exec
	s_or_b64 s[28:29], s[28:29], s[34:35]
	s_cmp_ge_i32 s62, s49
	s_mov_b32 s36, s62
	s_barrier
	s_cbranch_scc1 .LBB0_877

.LBB0_960:
	s_or_b64 exec, exec, s[10:11]
	s_add_i32 s48, s12, 2
	v_add_u32_e32 v3, s65, v230
	s_add_u32 s10, s26, s6
	ds_read_b128 v[140:143], v3
	ds_read_b128 v[144:147], v3 offset:1024
	ds_read_b128 v[148:151], v3 offset:2048
	ds_read_b128 v[152:155], v3 offset:3072
	s_addc_u32 s11, s27, s7
	s_add_u32 s10, s10, 0x100
	s_addc_u32 s11, s11, 0
	s_add_u32 s70, s33, s6
	s_addc_u32 s13, s43, s7
	s_cmp_eq_u32 s64, s12
	s_cselect_b32 s11, s14, s11
	s_cselect_b32 s10, s15, s10
	s_cselect_b32 s13, s45, s13
	s_cselect_b32 s12, s44, s70
	v_lshl_add_u64 v[164:165], v[136:137], 0, s[6:7]
	s_add_i32 m0, s55, 0xc000
	ds_read_b128 v[156:159], v232
	ds_read_b128 v[160:163], v232 offset:1024
	ds_read_b128 v[184:187], v232 offset:2048
	ds_read_b128 v[188:191], v232 offset:3072
	ds_read_b128 v[198:201], v232 offset:4096
	ds_read_b128 v[202:205], v232 offset:5120
	ds_read_b128 v[206:209], v232 offset:6144
	ds_read_b128 v[210:213], v232 offset:7168
	global_load_lds_dwordx4 v[164:165], off
	v_lshl_add_u64 v[164:165], v[138:139], 0, s[6:7]
	s_add_i32 m0, s55, 0xe000
	s_nop 0
	global_load_lds_dwordx4 v[164:165], off
	s_waitcnt lgkmcnt(8)
	s_barrier
	s_waitcnt lgkmcnt(0)
	s_waitcnt lgkmcnt(0)
	v_mfma_f32_16x16x32_bf16 v[130:133], v[140:143], v[156:159], v[130:133]
	v_mfma_f32_16x16x32_bf16 v[126:129], v[148:151], v[156:159], v[126:129]
	v_mfma_f32_16x16x32_bf16 v[122:125], v[140:143], v[184:187], v[122:125]
	v_mfma_f32_16x16x32_bf16 v[118:121], v[148:151], v[184:187], v[118:121]
	v_mfma_f32_16x16x32_bf16 v[114:117], v[140:143], v[198:201], v[114:117]
	v_mfma_f32_16x16x32_bf16 v[110:113], v[148:151], v[198:201], v[110:113]
	v_mfma_f32_16x16x32_bf16 v[106:109], v[140:143], v[206:209], v[106:109]
	v_mfma_f32_16x16x32_bf16 v[102:105], v[148:151], v[206:209], v[102:105]
	v_mfma_f32_16x16x32_bf16 v[130:133], v[144:147], v[160:163], v[130:133]
	v_mfma_f32_16x16x32_bf16 v[126:129], v[152:155], v[160:163], v[126:129]
	v_mfma_f32_16x16x32_bf16 v[122:125], v[144:147], v[188:191], v[122:125]
	v_mfma_f32_16x16x32_bf16 v[118:121], v[152:155], v[188:191], v[118:121]
	v_mfma_f32_16x16x32_bf16 v[114:117], v[144:147], v[202:205], v[114:117]
	v_mfma_f32_16x16x32_bf16 v[110:113], v[152:155], v[202:205], v[110:113]
	v_mfma_f32_16x16x32_bf16 v[106:109], v[144:147], v[210:213], v[106:109]
	v_mfma_f32_16x16x32_bf16 v[102:105], v[152:155], v[210:213], v[102:105]
	s_barrier
	s_add_i32 s70, s65, s54
	v_add_u32_e32 v3, s66, v230
	v_lshl_add_u64 v[164:165], s[12:13], 0, v[168:169]
	s_mov_b32 m0, s70
	ds_read_b128 v[214:217], v3
	ds_read_b128 v[218:221], v3 offset:1024
	ds_read_b128 v[222:225], v3 offset:2048
	ds_read_b128 v[226:229], v3 offset:3072
	global_load_lds_dwordx4 v[164:165], off
	v_lshl_add_u64 v[236:237], s[12:13], 0, v[172:173]
	s_add_i32 m0, s70, 0x2000
	s_nop 0
	global_load_lds_dwordx4 v[236:237], off
	s_barrier
	s_waitcnt lgkmcnt(0)
	s_waitcnt lgkmcnt(0)
	v_mfma_f32_16x16x32_bf16 v[98:101], v[214:217], v[156:159], v[98:101]
	v_mfma_f32_16x16x32_bf16 v[94:97], v[222:225], v[156:159], v[94:97]
	v_mfma_f32_16x16x32_bf16 v[90:93], v[214:217], v[184:187], v[90:93]
	v_mfma_f32_16x16x32_bf16 v[86:89], v[222:225], v[184:187], v[86:89]
	v_mfma_f32_16x16x32_bf16 v[82:85], v[214:217], v[198:201], v[82:85]
	v_mfma_f32_16x16x32_bf16 v[78:81], v[222:225], v[198:201], v[78:81]
	v_mfma_f32_16x16x32_bf16 v[74:77], v[214:217], v[206:209], v[74:77]
	v_mfma_f32_16x16x32_bf16 v[70:73], v[222:225], v[206:209], v[70:73]
	v_mfma_f32_16x16x32_bf16 v[98:101], v[218:221], v[160:163], v[98:101]
	v_mfma_f32_16x16x32_bf16 v[94:97], v[226:229], v[160:163], v[94:97]
	v_mfma_f32_16x16x32_bf16 v[90:93], v[218:221], v[188:191], v[90:93]
	v_mfma_f32_16x16x32_bf16 v[86:89], v[226:229], v[188:191], v[86:89]
	v_mfma_f32_16x16x32_bf16 v[82:85], v[218:221], v[202:205], v[82:85]
	v_mfma_f32_16x16x32_bf16 v[78:81], v[226:229], v[202:205], v[78:81]
	v_mfma_f32_16x16x32_bf16 v[74:77], v[218:221], v[210:213], v[74:77]
	v_mfma_f32_16x16x32_bf16 v[70:73], v[226:229], v[210:213], v[70:73]
	s_mov_b32 m0, s55
	v_lshl_add_u64 v[238:239], s[10:11], 0, v[166:167]
	s_barrier
	ds_read_b128 v[156:159], v232 offset:16384
	ds_read_b128 v[160:163], v232 offset:17408
	ds_read_b128 v[184:187], v232 offset:18432
	ds_read_b128 v[188:191], v232 offset:19456
	ds_read_b128 v[198:201], v232 offset:20480
	ds_read_b128 v[202:205], v232 offset:21504
	ds_read_b128 v[206:209], v232 offset:22528
	ds_read_b128 v[210:213], v232 offset:23552
	global_load_lds_dwordx4 v[238:239], off
	v_lshl_add_u64 v[240:241], s[10:11], 0, v[170:171]
	s_mov_b32 m0, s56
	s_nop 0
	global_load_lds_dwordx4 v[240:241], off
	s_barrier
	s_waitcnt lgkmcnt(0)
	s_waitcnt lgkmcnt(0)
	v_mfma_f32_16x16x32_bf16 v[66:69], v[140:143], v[156:159], v[66:69]
	v_mfma_f32_16x16x32_bf16 v[62:65], v[148:151], v[156:159], v[62:65]
	v_mfma_f32_16x16x32_bf16 v[58:61], v[140:143], v[184:187], v[58:61]
	v_mfma_f32_16x16x32_bf16 v[54:57], v[148:151], v[184:187], v[54:57]
	v_mfma_f32_16x16x32_bf16 v[50:53], v[140:143], v[198:201], v[50:53]
	v_mfma_f32_16x16x32_bf16 v[46:49], v[148:151], v[198:201], v[46:49]
	v_mfma_f32_16x16x32_bf16 v[42:45], v[140:143], v[206:209], v[42:45]
	v_mfma_f32_16x16x32_bf16 v[38:41], v[148:151], v[206:209], v[38:41]
	v_mfma_f32_16x16x32_bf16 v[66:69], v[144:147], v[160:163], v[66:69]
	v_mfma_f32_16x16x32_bf16 v[62:65], v[152:155], v[160:163], v[62:65]
	v_mfma_f32_16x16x32_bf16 v[58:61], v[144:147], v[188:191], v[58:61]
	v_mfma_f32_16x16x32_bf16 v[54:57], v[152:155], v[188:191], v[54:57]
	v_mfma_f32_16x16x32_bf16 v[50:53], v[144:147], v[202:205], v[50:53]
	v_mfma_f32_16x16x32_bf16 v[46:49], v[152:155], v[202:205], v[46:49]
	v_mfma_f32_16x16x32_bf16 v[42:45], v[144:147], v[210:213], v[42:45]
	v_mfma_f32_16x16x32_bf16 v[38:41], v[152:155], v[210:213], v[38:41]
	s_barrier
	s_add_u32 s12, s12, s20
	s_addc_u32 s13, s13, s21
	s_add_i32 s70, s66, s54
	v_lshl_add_u64 v[242:243], s[12:13], 0, v[168:169]
	s_mov_b32 m0, s70
	v_lshl_add_u64 v[244:245], s[12:13], 0, v[172:173]
	global_load_lds_dwordx4 v[242:243], off
	s_add_i32 m0, s70, 0x2000
	s_nop 0
	global_load_lds_dwordx4 v[244:245], off
	s_waitcnt vmcnt(6)
	s_barrier
	v_mfma_f32_16x16x32_bf16 v[34:37], v[214:217], v[156:159], v[34:37]
	v_mfma_f32_16x16x32_bf16 v[30:33], v[222:225], v[156:159], v[30:33]
	v_mfma_f32_16x16x32_bf16 v[26:29], v[214:217], v[184:187], v[26:29]
	v_mfma_f32_16x16x32_bf16 v[22:25], v[222:225], v[184:187], v[22:25]
	v_mfma_f32_16x16x32_bf16 v[18:21], v[214:217], v[198:201], v[18:21]
	v_mfma_f32_16x16x32_bf16 v[14:17], v[222:225], v[198:201], v[14:17]
	v_mfma_f32_16x16x32_bf16 v[10:13], v[214:217], v[206:209], v[10:13]
	v_mfma_f32_16x16x32_bf16 v[6:9], v[222:225], v[206:209], v[6:9]
	v_mfma_f32_16x16x32_bf16 v[34:37], v[218:221], v[160:163], v[34:37]
	v_mfma_f32_16x16x32_bf16 v[30:33], v[226:229], v[160:163], v[30:33]
	v_mfma_f32_16x16x32_bf16 v[26:29], v[218:221], v[188:191], v[26:29]
	v_mfma_f32_16x16x32_bf16 v[22:25], v[226:229], v[188:191], v[22:25]
	v_mfma_f32_16x16x32_bf16 v[18:21], v[218:221], v[202:205], v[18:21]
	v_mfma_f32_16x16x32_bf16 v[14:17], v[226:229], v[202:205], v[14:17]
	v_mfma_f32_16x16x32_bf16 v[10:13], v[218:221], v[210:213], v[10:13]
	v_mfma_f32_16x16x32_bf16 v[6:9], v[226:229], v[210:213], v[6:9]
	s_add_i32 s12, 0, 0x18000
	v_add_u32_e32 v3, s12, v230
	s_barrier
	ds_read_b128 v[140:143], v3
	ds_read_b128 v[144:147], v3 offset:1024
	ds_read_b128 v[148:151], v3 offset:2048
	ds_read_b128 v[152:155], v3 offset:3072
	s_add_u32 s10, s10, 0x80000
	s_addc_u32 s11, s11, 0
	s_mov_b32 m0, s57
	v_lshl_add_u64 v[214:215], s[10:11], 0, v[166:167]
	ds_read_b128 v[156:159], v232 offset:32768
	ds_read_b128 v[160:163], v232 offset:33792
	ds_read_b128 v[184:187], v232 offset:34816
	ds_read_b128 v[188:191], v232 offset:35840
	ds_read_b128 v[198:201], v232 offset:36864
	ds_read_b128 v[202:205], v232 offset:37888
	ds_read_b128 v[206:209], v232 offset:38912
	ds_read_b128 v[210:213], v232 offset:39936
	global_load_lds_dwordx4 v[214:215], off
	v_lshl_add_u64 v[214:215], s[10:11], 0, v[170:171]
	s_mov_b32 m0, s58
	s_nop 0
	global_load_lds_dwordx4 v[214:215], off
	s_waitcnt lgkmcnt(8)
	s_barrier
	s_waitcnt lgkmcnt(0)
	s_waitcnt lgkmcnt(0)
	v_mfma_f32_16x16x32_bf16 v[130:133], v[140:143], v[156:159], v[130:133]
	v_mfma_f32_16x16x32_bf16 v[126:129], v[148:151], v[156:159], v[126:129]
	v_mfma_f32_16x16x32_bf16 v[122:125], v[140:143], v[184:187], v[122:125]
	v_mfma_f32_16x16x32_bf16 v[118:121], v[148:151], v[184:187], v[118:121]
	v_mfma_f32_16x16x32_bf16 v[114:117], v[140:143], v[198:201], v[114:117]
	v_mfma_f32_16x16x32_bf16 v[110:113], v[148:151], v[198:201], v[110:113]
	v_mfma_f32_16x16x32_bf16 v[106:109], v[140:143], v[206:209], v[106:109]
	v_mfma_f32_16x16x32_bf16 v[102:105], v[148:151], v[206:209], v[102:105]
	v_mfma_f32_16x16x32_bf16 v[130:133], v[144:147], v[160:163], v[130:133]
	v_mfma_f32_16x16x32_bf16 v[126:129], v[152:155], v[160:163], v[126:129]
	v_mfma_f32_16x16x32_bf16 v[122:125], v[144:147], v[188:191], v[122:125]
	v_mfma_f32_16x16x32_bf16 v[118:121], v[152:155], v[188:191], v[118:121]
	v_mfma_f32_16x16x32_bf16 v[114:117], v[144:147], v[202:205], v[114:117]
	v_mfma_f32_16x16x32_bf16 v[110:113], v[152:155], v[202:205], v[110:113]
	v_mfma_f32_16x16x32_bf16 v[106:109], v[144:147], v[210:213], v[106:109]
	v_mfma_f32_16x16x32_bf16 v[102:105], v[152:155], v[210:213], v[102:105]
	s_barrier
	s_add_i32 s10, 0, 0x1c000
	s_add_i32 s11, s12, s54
	v_add_u32_e32 v3, s10, v230
	v_lshl_add_u64 v[164:165], v[164:165], 0, s[38:39]
	s_mov_b32 m0, s11
	ds_read_b128 v[214:217], v3
	ds_read_b128 v[218:221], v3 offset:1024
	ds_read_b128 v[222:225], v3 offset:2048
	ds_read_b128 v[226:229], v3 offset:3072
	global_load_lds_dwordx4 v[164:165], off
	v_lshl_add_u64 v[164:165], v[236:237], 0, s[38:39]
	s_add_i32 m0, s11, 0x2000
	s_nop 0
	global_load_lds_dwordx4 v[164:165], off
	s_barrier
	s_waitcnt lgkmcnt(0)
	s_waitcnt lgkmcnt(0)
	v_mfma_f32_16x16x32_bf16 v[98:101], v[214:217], v[156:159], v[98:101]
	v_mfma_f32_16x16x32_bf16 v[94:97], v[222:225], v[156:159], v[94:97]
	v_mfma_f32_16x16x32_bf16 v[90:93], v[214:217], v[184:187], v[90:93]
	v_mfma_f32_16x16x32_bf16 v[86:89], v[222:225], v[184:187], v[86:89]
	v_mfma_f32_16x16x32_bf16 v[82:85], v[214:217], v[198:201], v[82:85]
	v_mfma_f32_16x16x32_bf16 v[78:81], v[222:225], v[198:201], v[78:81]
	v_mfma_f32_16x16x32_bf16 v[74:77], v[214:217], v[206:209], v[74:77]
	v_mfma_f32_16x16x32_bf16 v[70:73], v[222:225], v[206:209], v[70:73]
	v_mfma_f32_16x16x32_bf16 v[98:101], v[218:221], v[160:163], v[98:101]
	v_mfma_f32_16x16x32_bf16 v[94:97], v[226:229], v[160:163], v[94:97]
	v_mfma_f32_16x16x32_bf16 v[90:93], v[218:221], v[188:191], v[90:93]
	v_mfma_f32_16x16x32_bf16 v[86:89], v[226:229], v[188:191], v[86:89]
	v_mfma_f32_16x16x32_bf16 v[82:85], v[218:221], v[202:205], v[82:85]
	v_mfma_f32_16x16x32_bf16 v[78:81], v[226:229], v[202:205], v[78:81]
	v_mfma_f32_16x16x32_bf16 v[74:77], v[218:221], v[210:213], v[74:77]
	v_mfma_f32_16x16x32_bf16 v[70:73], v[226:229], v[210:213], v[70:73]
	s_mov_b32 m0, s62
	v_lshl_add_u64 v[164:165], v[238:239], 0, s[38:39]
	s_barrier
	ds_read_b128 v[156:159], v232 offset:49152
	ds_read_b128 v[160:163], v232 offset:50176
	ds_read_b128 v[184:187], v232 offset:51200
	ds_read_b128 v[188:191], v232 offset:52224
	ds_read_b128 v[198:201], v232 offset:53248
	ds_read_b128 v[202:205], v232 offset:54272
	ds_read_b128 v[206:209], v232 offset:55296
	ds_read_b128 v[210:213], v232 offset:56320
	global_load_lds_dwordx4 v[164:165], off
	v_lshl_add_u64 v[164:165], v[240:241], 0, s[38:39]
	s_mov_b32 m0, s63
	s_nop 0
	global_load_lds_dwordx4 v[164:165], off
	s_barrier
	s_waitcnt lgkmcnt(0)
	s_waitcnt lgkmcnt(0)
	v_mfma_f32_16x16x32_bf16 v[66:69], v[140:143], v[156:159], v[66:69]
	v_mfma_f32_16x16x32_bf16 v[62:65], v[148:151], v[156:159], v[62:65]
	v_mfma_f32_16x16x32_bf16 v[58:61], v[140:143], v[184:187], v[58:61]
	v_mfma_f32_16x16x32_bf16 v[54:57], v[148:151], v[184:187], v[54:57]
	v_mfma_f32_16x16x32_bf16 v[50:53], v[140:143], v[198:201], v[50:53]
	v_mfma_f32_16x16x32_bf16 v[46:49], v[148:151], v[198:201], v[46:49]
	v_mfma_f32_16x16x32_bf16 v[42:45], v[140:143], v[206:209], v[42:45]
	v_mfma_f32_16x16x32_bf16 v[38:41], v[148:151], v[206:209], v[38:41]
	v_mfma_f32_16x16x32_bf16 v[66:69], v[144:147], v[160:163], v[66:69]
	v_mfma_f32_16x16x32_bf16 v[62:65], v[152:155], v[160:163], v[62:65]
	v_mfma_f32_16x16x32_bf16 v[58:61], v[144:147], v[188:191], v[58:61]
	v_mfma_f32_16x16x32_bf16 v[54:57], v[152:155], v[188:191], v[54:57]
	v_mfma_f32_16x16x32_bf16 v[50:53], v[144:147], v[202:205], v[50:53]
	v_mfma_f32_16x16x32_bf16 v[46:49], v[152:155], v[202:205], v[46:49]
	v_mfma_f32_16x16x32_bf16 v[42:45], v[144:147], v[210:213], v[42:45]
	v_mfma_f32_16x16x32_bf16 v[38:41], v[152:155], v[210:213], v[38:41]
	s_barrier
	s_add_i32 s10, s10, s54
	v_lshl_add_u64 v[140:141], v[242:243], 0, s[38:39]
	s_mov_b32 m0, s10
	s_nop 0
	global_load_lds_dwordx4 v[140:141], off
	v_lshl_add_u64 v[140:141], v[244:245], 0, s[38:39]
	s_add_i32 m0, s10, 0x2000
	s_nop 0
	global_load_lds_dwordx4 v[140:141], off
	s_waitcnt vmcnt(6)
	s_barrier
	v_mfma_f32_16x16x32_bf16 v[34:37], v[214:217], v[156:159], v[34:37]
	v_mfma_f32_16x16x32_bf16 v[30:33], v[222:225], v[156:159], v[30:33]
	v_mfma_f32_16x16x32_bf16 v[26:29], v[214:217], v[184:187], v[26:29]
	v_mfma_f32_16x16x32_bf16 v[22:25], v[222:225], v[184:187], v[22:25]
	v_mfma_f32_16x16x32_bf16 v[18:21], v[214:217], v[198:201], v[18:21]
	v_mfma_f32_16x16x32_bf16 v[14:17], v[222:225], v[198:201], v[14:17]
	v_mfma_f32_16x16x32_bf16 v[10:13], v[214:217], v[206:209], v[10:13]
	v_mfma_f32_16x16x32_bf16 v[6:9], v[222:225], v[206:209], v[6:9]
	v_mfma_f32_16x16x32_bf16 v[34:37], v[218:221], v[160:163], v[34:37]
	v_mfma_f32_16x16x32_bf16 v[30:33], v[226:229], v[160:163], v[30:33]
	v_mfma_f32_16x16x32_bf16 v[26:29], v[218:221], v[188:191], v[26:29]
	v_mfma_f32_16x16x32_bf16 v[22:25], v[226:229], v[188:191], v[22:25]
	v_mfma_f32_16x16x32_bf16 v[18:21], v[218:221], v[202:205], v[18:21]
	v_mfma_f32_16x16x32_bf16 v[14:17], v[226:229], v[202:205], v[14:17]
	v_mfma_f32_16x16x32_bf16 v[10:13], v[218:221], v[210:213], v[10:13]
	v_mfma_f32_16x16x32_bf16 v[6:9], v[226:229], v[210:213], v[6:9]
	s_add_u32 s6, s6, 0x100
	s_addc_u32 s7, s7, 0
	s_andn2_b64 s[0:1], s[0:1], exec
	s_and_b64 s[10:11], s[8:9], exec
	s_or_b64 s[0:1], s[0:1], s[10:11]
	s_cmp_ge_i32 s48, s59
	s_barrier
	s_cbranch_scc1 .LBB0_962
	s_mov_b32 s12, s48
	s_branch .LBB0_958

.LBB0_1037:
	ds_read_b128 v[146:149], v161
	ds_read_b128 v[150:153], v161 offset:1024
	ds_read_b128 v[154:157], v161 offset:2048
	ds_read_b128 v[166:169], v161 offset:3072
	s_add_i32 s57, s26, 2
	s_add_u32 s28, s6, 0xfff80080
	s_addc_u32 s27, s7, -1
	s_cmp_eq_u32 s46, s26
	s_cselect_b32 s26, s21, s28
	s_cselect_b32 s27, s1, s27
	s_cselect_b32 s29, s23, s56
	s_cselect_b32 s28, s22, s33
	v_lshl_add_u64 v[202:203], s[6:7], 0, v[138:139]
	s_add_i32 m0, s38, 0xc000
	ds_read_b128 v[170:173], v162
	ds_read_b128 v[174:177], v162 offset:1024
	ds_read_b128 v[178:181], v162 offset:2048
	ds_read_b128 v[182:185], v162 offset:3072
	ds_read_b128 v[186:189], v162 offset:4096
	ds_read_b128 v[190:193], v162 offset:5120
	ds_read_b128 v[194:197], v162 offset:6144
	ds_read_b128 v[198:201], v162 offset:7168
	global_load_lds_dwordx4 v[202:203], off
	v_lshl_add_u64 v[202:203], s[6:7], 0, v[140:141]
	s_add_i32 m0, s38, 0xe000
	s_nop 0
	global_load_lds_dwordx4 v[202:203], off
	s_waitcnt lgkmcnt(8)
	s_barrier
	s_waitcnt lgkmcnt(0)
	s_waitcnt lgkmcnt(0)
	v_mfma_f32_16x16x32_bf16 v[126:129], v[146:149], v[170:173], v[126:129]
	v_mfma_f32_16x16x32_bf16 v[122:125], v[154:157], v[170:173], v[122:125]
	v_mfma_f32_16x16x32_bf16 v[110:113], v[146:149], v[178:181], v[110:113]
	v_mfma_f32_16x16x32_bf16 v[106:109], v[154:157], v[178:181], v[106:109]
	v_mfma_f32_16x16x32_bf16 v[94:97], v[146:149], v[186:189], v[94:97]
	v_mfma_f32_16x16x32_bf16 v[90:93], v[154:157], v[186:189], v[90:93]
	v_mfma_f32_16x16x32_bf16 v[78:81], v[146:149], v[194:197], v[78:81]
	v_mfma_f32_16x16x32_bf16 v[74:77], v[154:157], v[194:197], v[74:77]
	v_mfma_f32_16x16x32_bf16 v[126:129], v[150:153], v[174:177], v[126:129]
	v_mfma_f32_16x16x32_bf16 v[122:125], v[166:169], v[174:177], v[122:125]
	v_mfma_f32_16x16x32_bf16 v[110:113], v[150:153], v[182:185], v[110:113]
	v_mfma_f32_16x16x32_bf16 v[106:109], v[166:169], v[182:185], v[106:109]
	v_mfma_f32_16x16x32_bf16 v[94:97], v[150:153], v[190:193], v[94:97]
	v_mfma_f32_16x16x32_bf16 v[90:93], v[166:169], v[190:193], v[90:93]
	v_mfma_f32_16x16x32_bf16 v[78:81], v[150:153], v[198:201], v[78:81]
	v_mfma_f32_16x16x32_bf16 v[74:77], v[166:169], v[198:201], v[74:77]
	s_barrier
	s_add_i32 s58, s50, s37
	v_lshl_add_u64 v[218:219], s[28:29], 0, v[132:133]
	s_mov_b32 m0, s58
	ds_read_b128 v[202:205], v163
	ds_read_b128 v[206:209], v163 offset:1024
	ds_read_b128 v[210:213], v163 offset:2048
	ds_read_b128 v[214:217], v163 offset:3072
	global_load_lds_dwordx4 v[218:219], off
	v_lshl_add_u64 v[220:221], s[28:29], 0, v[136:137]
	s_add_i32 m0, s58, 0x2000
	s_nop 0
	global_load_lds_dwordx4 v[220:221], off
	s_barrier
	s_waitcnt lgkmcnt(0)
	s_waitcnt lgkmcnt(0)
	v_mfma_f32_16x16x32_bf16 v[118:121], v[202:205], v[170:173], v[118:121]
	v_mfma_f32_16x16x32_bf16 v[114:117], v[210:213], v[170:173], v[114:117]
	v_mfma_f32_16x16x32_bf16 v[102:105], v[202:205], v[178:181], v[102:105]
	v_mfma_f32_16x16x32_bf16 v[98:101], v[210:213], v[178:181], v[98:101]
	v_mfma_f32_16x16x32_bf16 v[86:89], v[202:205], v[186:189], v[86:89]
	v_mfma_f32_16x16x32_bf16 v[82:85], v[210:213], v[186:189], v[82:85]
	v_mfma_f32_16x16x32_bf16 v[70:73], v[202:205], v[194:197], v[70:73]
	v_mfma_f32_16x16x32_bf16 v[66:69], v[210:213], v[194:197], v[66:69]
	v_mfma_f32_16x16x32_bf16 v[118:121], v[206:209], v[174:177], v[118:121]
	v_mfma_f32_16x16x32_bf16 v[114:117], v[214:217], v[174:177], v[114:117]
	v_mfma_f32_16x16x32_bf16 v[102:105], v[206:209], v[182:185], v[102:105]
	v_mfma_f32_16x16x32_bf16 v[98:101], v[214:217], v[182:185], v[98:101]
	v_mfma_f32_16x16x32_bf16 v[86:89], v[206:209], v[190:193], v[86:89]
	v_mfma_f32_16x16x32_bf16 v[82:85], v[214:217], v[190:193], v[82:85]
	v_mfma_f32_16x16x32_bf16 v[70:73], v[206:209], v[198:201], v[70:73]
	v_mfma_f32_16x16x32_bf16 v[66:69], v[214:217], v[198:201], v[66:69]
	s_mov_b32 m0, s38
	v_lshl_add_u64 v[222:223], s[26:27], 0, v[130:131]
	s_barrier
	ds_read_b128 v[170:173], v162 offset:16384
	ds_read_b128 v[174:177], v162 offset:17408
	ds_read_b128 v[178:181], v162 offset:18432
	ds_read_b128 v[182:185], v162 offset:19456
	ds_read_b128 v[186:189], v162 offset:20480
	ds_read_b128 v[190:193], v162 offset:21504
	ds_read_b128 v[194:197], v162 offset:22528
	ds_read_b128 v[198:201], v162 offset:23552
	global_load_lds_dwordx4 v[222:223], off
	v_lshl_add_u64 v[224:225], s[26:27], 0, v[134:135]
	s_mov_b32 m0, s39
	s_nop 0
	global_load_lds_dwordx4 v[224:225], off
	s_barrier
	s_waitcnt lgkmcnt(0)
	s_waitcnt lgkmcnt(0)
	v_mfma_f32_16x16x32_bf16 v[62:65], v[146:149], v[170:173], v[62:65]
	v_mfma_f32_16x16x32_bf16 v[58:61], v[154:157], v[170:173], v[58:61]
	v_mfma_f32_16x16x32_bf16 v[46:49], v[146:149], v[178:181], v[46:49]
	v_mfma_f32_16x16x32_bf16 v[42:45], v[154:157], v[178:181], v[42:45]
	v_mfma_f32_16x16x32_bf16 v[30:33], v[146:149], v[186:189], v[30:33]
	v_mfma_f32_16x16x32_bf16 v[26:29], v[154:157], v[186:189], v[26:29]
	v_mfma_f32_16x16x32_bf16 v[14:17], v[146:149], v[194:197], v[14:17]
	v_mfma_f32_16x16x32_bf16 v[10:13], v[154:157], v[194:197], v[10:13]
	v_mfma_f32_16x16x32_bf16 v[62:65], v[150:153], v[174:177], v[62:65]
	v_mfma_f32_16x16x32_bf16 v[58:61], v[166:169], v[174:177], v[58:61]
	v_mfma_f32_16x16x32_bf16 v[46:49], v[150:153], v[182:185], v[46:49]
	v_mfma_f32_16x16x32_bf16 v[42:45], v[166:169], v[182:185], v[42:45]
	v_mfma_f32_16x16x32_bf16 v[30:33], v[150:153], v[190:193], v[30:33]
	v_mfma_f32_16x16x32_bf16 v[26:29], v[166:169], v[190:193], v[26:29]
	v_mfma_f32_16x16x32_bf16 v[14:17], v[150:153], v[198:201], v[14:17]
	v_mfma_f32_16x16x32_bf16 v[10:13], v[166:169], v[198:201], v[10:13]
	s_barrier
	s_add_u32 s28, s28, s12
	s_addc_u32 s29, s29, s13
	s_add_i32 s58, s51, s37
	v_lshl_add_u64 v[226:227], s[28:29], 0, v[132:133]
	s_mov_b32 m0, s58
	v_lshl_add_u64 v[228:229], s[28:29], 0, v[136:137]
	global_load_lds_dwordx4 v[226:227], off
	s_add_i32 m0, s58, 0x2000
	s_nop 0
	global_load_lds_dwordx4 v[228:229], off
	s_waitcnt vmcnt(6)
	s_barrier
	v_mfma_f32_16x16x32_bf16 v[54:57], v[202:205], v[170:173], v[54:57]
	v_mfma_f32_16x16x32_bf16 v[50:53], v[210:213], v[170:173], v[50:53]
	v_mfma_f32_16x16x32_bf16 v[38:41], v[202:205], v[178:181], v[38:41]
	v_mfma_f32_16x16x32_bf16 v[34:37], v[210:213], v[178:181], v[34:37]
	v_mfma_f32_16x16x32_bf16 v[22:25], v[202:205], v[186:189], v[22:25]
	v_mfma_f32_16x16x32_bf16 v[18:21], v[210:213], v[186:189], v[18:21]
	v_mfma_f32_16x16x32_bf16 v[6:9], v[202:205], v[194:197], v[6:9]
	v_mfma_f32_16x16x32_bf16 v[2:5], v[210:213], v[194:197], v[2:5]
	v_mfma_f32_16x16x32_bf16 v[54:57], v[206:209], v[174:177], v[54:57]
	v_mfma_f32_16x16x32_bf16 v[50:53], v[214:217], v[174:177], v[50:53]
	v_mfma_f32_16x16x32_bf16 v[38:41], v[206:209], v[182:185], v[38:41]
	v_mfma_f32_16x16x32_bf16 v[34:37], v[214:217], v[182:185], v[34:37]
	v_mfma_f32_16x16x32_bf16 v[22:25], v[206:209], v[190:193], v[22:25]
	v_mfma_f32_16x16x32_bf16 v[18:21], v[214:217], v[190:193], v[18:21]
	v_mfma_f32_16x16x32_bf16 v[6:9], v[206:209], v[198:201], v[6:9]
	v_mfma_f32_16x16x32_bf16 v[2:5], v[214:217], v[198:201], v[2:5]
	s_add_i32 s28, 0, 0x18000
	v_add_u32_e32 v165, s28, v159
	s_barrier
	ds_read_b128 v[146:149], v165
	ds_read_b128 v[150:153], v165 offset:1024
	ds_read_b128 v[154:157], v165 offset:2048
	ds_read_b128 v[166:169], v165 offset:3072
	s_add_u32 s26, s26, 0x80000
	s_addc_u32 s27, s27, 0
	s_mov_b32 m0, s40
	v_lshl_add_u64 v[202:203], s[26:27], 0, v[130:131]
	ds_read_b128 v[170:173], v162 offset:32768
	ds_read_b128 v[174:177], v162 offset:33792
	ds_read_b128 v[178:181], v162 offset:34816
	ds_read_b128 v[182:185], v162 offset:35840
	ds_read_b128 v[186:189], v162 offset:36864
	ds_read_b128 v[190:193], v162 offset:37888
	ds_read_b128 v[194:197], v162 offset:38912
	ds_read_b128 v[198:201], v162 offset:39936
	global_load_lds_dwordx4 v[202:203], off
	v_lshl_add_u64 v[202:203], s[26:27], 0, v[134:135]
	s_mov_b32 m0, s41
	s_nop 0
	global_load_lds_dwordx4 v[202:203], off
	s_waitcnt lgkmcnt(8)
	s_barrier
	s_waitcnt lgkmcnt(0)
	s_waitcnt lgkmcnt(0)
	v_mfma_f32_16x16x32_bf16 v[126:129], v[146:149], v[170:173], v[126:129]
	v_mfma_f32_16x16x32_bf16 v[122:125], v[154:157], v[170:173], v[122:125]
	v_mfma_f32_16x16x32_bf16 v[110:113], v[146:149], v[178:181], v[110:113]
	v_mfma_f32_16x16x32_bf16 v[106:109], v[154:157], v[178:181], v[106:109]
	v_mfma_f32_16x16x32_bf16 v[94:97], v[146:149], v[186:189], v[94:97]
	v_mfma_f32_16x16x32_bf16 v[90:93], v[154:157], v[186:189], v[90:93]
	v_mfma_f32_16x16x32_bf16 v[78:81], v[146:149], v[194:197], v[78:81]
	v_mfma_f32_16x16x32_bf16 v[74:77], v[154:157], v[194:197], v[74:77]
	v_mfma_f32_16x16x32_bf16 v[126:129], v[150:153], v[174:177], v[126:129]
	v_mfma_f32_16x16x32_bf16 v[122:125], v[166:169], v[174:177], v[122:125]
	v_mfma_f32_16x16x32_bf16 v[110:113], v[150:153], v[182:185], v[110:113]
	v_mfma_f32_16x16x32_bf16 v[106:109], v[166:169], v[182:185], v[106:109]
	v_mfma_f32_16x16x32_bf16 v[94:97], v[150:153], v[190:193], v[94:97]
	v_mfma_f32_16x16x32_bf16 v[90:93], v[166:169], v[190:193], v[90:93]
	v_mfma_f32_16x16x32_bf16 v[78:81], v[150:153], v[198:201], v[78:81]
	v_mfma_f32_16x16x32_bf16 v[74:77], v[166:169], v[198:201], v[74:77]
	s_barrier
	s_add_i32 s26, 0, 0x1c000
	s_add_i32 s27, s28, s37
	v_add_u32_e32 v165, s26, v159
	v_lshl_add_u64 v[218:219], v[218:219], 0, s[18:19]
	s_mov_b32 m0, s27
	ds_read_b128 v[202:205], v165
	ds_read_b128 v[206:209], v165 offset:1024
	ds_read_b128 v[210:213], v165 offset:2048
	ds_read_b128 v[214:217], v165 offset:3072
	global_load_lds_dwordx4 v[218:219], off
	v_lshl_add_u64 v[218:219], v[220:221], 0, s[18:19]
	s_add_i32 m0, s27, 0x2000
	s_nop 0
	global_load_lds_dwordx4 v[218:219], off
	s_barrier
	s_waitcnt lgkmcnt(0)
	s_waitcnt lgkmcnt(0)
	v_mfma_f32_16x16x32_bf16 v[118:121], v[202:205], v[170:173], v[118:121]
	v_mfma_f32_16x16x32_bf16 v[114:117], v[210:213], v[170:173], v[114:117]
	v_mfma_f32_16x16x32_bf16 v[102:105], v[202:205], v[178:181], v[102:105]
	v_mfma_f32_16x16x32_bf16 v[98:101], v[210:213], v[178:181], v[98:101]
	v_mfma_f32_16x16x32_bf16 v[86:89], v[202:205], v[186:189], v[86:89]
	v_mfma_f32_16x16x32_bf16 v[82:85], v[210:213], v[186:189], v[82:85]
	v_mfma_f32_16x16x32_bf16 v[70:73], v[202:205], v[194:197], v[70:73]
	v_mfma_f32_16x16x32_bf16 v[66:69], v[210:213], v[194:197], v[66:69]
	v_mfma_f32_16x16x32_bf16 v[118:121], v[206:209], v[174:177], v[118:121]
	v_mfma_f32_16x16x32_bf16 v[114:117], v[214:217], v[174:177], v[114:117]
	v_mfma_f32_16x16x32_bf16 v[102:105], v[206:209], v[182:185], v[102:105]
	v_mfma_f32_16x16x32_bf16 v[98:101], v[214:217], v[182:185], v[98:101]
	v_mfma_f32_16x16x32_bf16 v[86:89], v[206:209], v[190:193], v[86:89]
	v_mfma_f32_16x16x32_bf16 v[82:85], v[214:217], v[190:193], v[82:85]
	v_mfma_f32_16x16x32_bf16 v[70:73], v[206:209], v[198:201], v[70:73]
	v_mfma_f32_16x16x32_bf16 v[66:69], v[214:217], v[198:201], v[66:69]
	s_mov_b32 m0, s43
	v_lshl_add_u64 v[218:219], v[222:223], 0, s[18:19]
	s_barrier
	ds_read_b128 v[170:173], v162 offset:49152
	ds_read_b128 v[174:177], v162 offset:50176
	ds_read_b128 v[178:181], v162 offset:51200
	ds_read_b128 v[182:185], v162 offset:52224
	ds_read_b128 v[186:189], v162 offset:53248
	ds_read_b128 v[190:193], v162 offset:54272
	ds_read_b128 v[194:197], v162 offset:55296
	ds_read_b128 v[198:201], v162 offset:56320
	global_load_lds_dwordx4 v[218:219], off
	v_lshl_add_u64 v[218:219], v[224:225], 0, s[18:19]
	s_mov_b32 m0, s44
	s_nop 0
	global_load_lds_dwordx4 v[218:219], off
	s_barrier
	s_waitcnt lgkmcnt(0)
	s_waitcnt lgkmcnt(0)
	v_mfma_f32_16x16x32_bf16 v[62:65], v[146:149], v[170:173], v[62:65]
	v_mfma_f32_16x16x32_bf16 v[58:61], v[154:157], v[170:173], v[58:61]
	v_mfma_f32_16x16x32_bf16 v[46:49], v[146:149], v[178:181], v[46:49]
	v_mfma_f32_16x16x32_bf16 v[42:45], v[154:157], v[178:181], v[42:45]
	v_mfma_f32_16x16x32_bf16 v[30:33], v[146:149], v[186:189], v[30:33]
	v_mfma_f32_16x16x32_bf16 v[26:29], v[154:157], v[186:189], v[26:29]
	v_mfma_f32_16x16x32_bf16 v[14:17], v[146:149], v[194:197], v[14:17]
	v_mfma_f32_16x16x32_bf16 v[10:13], v[154:157], v[194:197], v[10:13]
	v_mfma_f32_16x16x32_bf16 v[62:65], v[150:153], v[174:177], v[62:65]
	v_mfma_f32_16x16x32_bf16 v[58:61], v[166:169], v[174:177], v[58:61]
	v_mfma_f32_16x16x32_bf16 v[46:49], v[150:153], v[182:185], v[46:49]
	v_mfma_f32_16x16x32_bf16 v[42:45], v[166:169], v[182:185], v[42:45]
	v_mfma_f32_16x16x32_bf16 v[30:33], v[150:153], v[190:193], v[30:33]
	v_mfma_f32_16x16x32_bf16 v[26:29], v[166:169], v[190:193], v[26:29]
	v_mfma_f32_16x16x32_bf16 v[14:17], v[150:153], v[198:201], v[14:17]
	v_mfma_f32_16x16x32_bf16 v[10:13], v[166:169], v[198:201], v[10:13]
	s_barrier
	s_add_i32 s26, s26, s37
	v_lshl_add_u64 v[146:147], v[226:227], 0, s[18:19]
	s_mov_b32 m0, s26
	s_nop 0
	global_load_lds_dwordx4 v[146:147], off
	v_lshl_add_u64 v[146:147], v[228:229], 0, s[18:19]
	s_add_i32 m0, s26, 0x2000
	s_nop 0
	global_load_lds_dwordx4 v[146:147], off
	s_waitcnt vmcnt(6)
	s_barrier
	v_mfma_f32_16x16x32_bf16 v[54:57], v[202:205], v[170:173], v[54:57]
	v_mfma_f32_16x16x32_bf16 v[50:53], v[210:213], v[170:173], v[50:53]
	v_mfma_f32_16x16x32_bf16 v[38:41], v[202:205], v[178:181], v[38:41]
	v_mfma_f32_16x16x32_bf16 v[34:37], v[210:213], v[178:181], v[34:37]
	v_mfma_f32_16x16x32_bf16 v[22:25], v[202:205], v[186:189], v[22:25]
	v_mfma_f32_16x16x32_bf16 v[18:21], v[210:213], v[186:189], v[18:21]
	v_mfma_f32_16x16x32_bf16 v[6:9], v[202:205], v[194:197], v[6:9]
	v_mfma_f32_16x16x32_bf16 v[2:5], v[210:213], v[194:197], v[2:5]
	v_mfma_f32_16x16x32_bf16 v[54:57], v[206:209], v[174:177], v[54:57]
	v_mfma_f32_16x16x32_bf16 v[50:53], v[214:217], v[174:177], v[50:53]
	v_mfma_f32_16x16x32_bf16 v[38:41], v[206:209], v[182:185], v[38:41]
	v_mfma_f32_16x16x32_bf16 v[34:37], v[214:217], v[182:185], v[34:37]
	v_mfma_f32_16x16x32_bf16 v[22:25], v[206:209], v[190:193], v[22:25]
	v_mfma_f32_16x16x32_bf16 v[18:21], v[214:217], v[190:193], v[18:21]
	v_mfma_f32_16x16x32_bf16 v[6:9], v[206:209], v[198:201], v[6:9]
	v_mfma_f32_16x16x32_bf16 v[2:5], v[214:217], v[198:201], v[2:5]
	s_add_u32 s6, s6, 0x100
	s_addc_u32 s7, s7, 0
	s_add_u32 s33, s33, 0x100
	s_addc_u32 s56, s56, 0
	s_cmp_ge_i32 s57, s45
	s_mov_b32 s26, s57
	s_barrier
	s_cbranch_scc0 .LBB0_1037

.LBB0_1481:
	s_or_b64 exec, exec, s[44:45]
	s_add_i32 s72, s46, 2
	s_add_u32 s44, s18, s40
	v_add_u32_e32 v3, s65, v181
	s_addc_u32 s45, s19, s41
	ds_read_b128 v[162:165], v3
	ds_read_b128 v[186:189], v3 offset:1024
	ds_read_b128 v[190:193], v3 offset:2048
	ds_read_b128 v[194:197], v3 offset:3072
	s_add_u32 s44, s44, 0x100
	s_addc_u32 s45, s45, 0
	s_add_u32 s73, s33, s40
	s_addc_u32 s47, s71, s41
	s_cmp_eq_u32 s64, s46
	s_cselect_b32 s46, s0, s73
	s_cselect_b32 s45, s7, s45
	s_cselect_b32 s44, s6, s44
	s_cselect_b32 s47, s1, s47
	v_lshl_add_u64 v[166:167], v[138:139], 0, s[40:41]
	s_add_i32 m0, s55, 0xc000
	ds_read_b128 v[198:201], v183
	ds_read_b128 v[202:205], v183 offset:1024
	ds_read_b128 v[206:209], v183 offset:2048
	ds_read_b128 v[210:213], v183 offset:3072
	ds_read_b128 v[214:217], v183 offset:4096
	ds_read_b128 v[218:221], v183 offset:5120
	ds_read_b128 v[222:225], v183 offset:6144
	ds_read_b128 v[226:229], v183 offset:7168
	global_load_lds_dwordx4 v[166:167], off
	v_lshl_add_u64 v[166:167], v[140:141], 0, s[40:41]
	s_add_i32 m0, s55, 0xe000
	s_nop 0
	global_load_lds_dwordx4 v[166:167], off
	s_waitcnt lgkmcnt(8)
	s_barrier
	s_waitcnt lgkmcnt(0)
	s_waitcnt lgkmcnt(0)
	v_mfma_f32_16x16x32_bf16 v[130:133], v[162:165], v[198:201], v[130:133]
	v_mfma_f32_16x16x32_bf16 v[126:129], v[190:193], v[198:201], v[126:129]
	v_mfma_f32_16x16x32_bf16 v[122:125], v[162:165], v[206:209], v[122:125]
	v_mfma_f32_16x16x32_bf16 v[118:121], v[190:193], v[206:209], v[118:121]
	v_mfma_f32_16x16x32_bf16 v[114:117], v[162:165], v[214:217], v[114:117]
	v_mfma_f32_16x16x32_bf16 v[110:113], v[190:193], v[214:217], v[110:113]
	v_mfma_f32_16x16x32_bf16 v[106:109], v[162:165], v[222:225], v[106:109]
	v_mfma_f32_16x16x32_bf16 v[98:101], v[190:193], v[222:225], v[98:101]
	v_mfma_f32_16x16x32_bf16 v[130:133], v[186:189], v[202:205], v[130:133]
	v_mfma_f32_16x16x32_bf16 v[126:129], v[194:197], v[202:205], v[126:129]
	v_mfma_f32_16x16x32_bf16 v[122:125], v[186:189], v[210:213], v[122:125]
	v_mfma_f32_16x16x32_bf16 v[118:121], v[194:197], v[210:213], v[118:121]
	v_mfma_f32_16x16x32_bf16 v[114:117], v[186:189], v[218:221], v[114:117]
	v_mfma_f32_16x16x32_bf16 v[110:113], v[194:197], v[218:221], v[110:113]
	v_mfma_f32_16x16x32_bf16 v[106:109], v[186:189], v[226:229], v[106:109]
	v_mfma_f32_16x16x32_bf16 v[98:101], v[194:197], v[226:229], v[98:101]
	s_barrier
	s_add_i32 s73, s65, s54
	v_add_u32_e32 v3, s66, v181
	v_lshl_add_u64 v[166:167], s[46:47], 0, v[150:151]
	s_mov_b32 m0, s73
	ds_read_b128 v[230:233], v3
	ds_read_b128 v[234:237], v3 offset:1024
	ds_read_b128 v[238:241], v3 offset:2048
	ds_read_b128 v[242:245], v3 offset:3072
	global_load_lds_dwordx4 v[166:167], off
	v_lshl_add_u64 v[246:247], s[46:47], 0, v[154:155]
	s_add_i32 m0, s73, 0x2000
	s_nop 0
	global_load_lds_dwordx4 v[246:247], off
	s_barrier
	s_waitcnt lgkmcnt(0)
	s_waitcnt lgkmcnt(0)
	v_mfma_f32_16x16x32_bf16 v[102:105], v[230:233], v[198:201], v[102:105]
	v_mfma_f32_16x16x32_bf16 v[94:97], v[238:241], v[198:201], v[94:97]
	v_mfma_f32_16x16x32_bf16 v[90:93], v[230:233], v[206:209], v[90:93]
	v_mfma_f32_16x16x32_bf16 v[86:89], v[238:241], v[206:209], v[86:89]
	v_mfma_f32_16x16x32_bf16 v[82:85], v[230:233], v[214:217], v[82:85]
	v_mfma_f32_16x16x32_bf16 v[78:81], v[238:241], v[214:217], v[78:81]
	v_mfma_f32_16x16x32_bf16 v[74:77], v[230:233], v[222:225], v[74:77]
	v_mfma_f32_16x16x32_bf16 v[70:73], v[238:241], v[222:225], v[70:73]
	v_mfma_f32_16x16x32_bf16 v[102:105], v[234:237], v[202:205], v[102:105]
	v_mfma_f32_16x16x32_bf16 v[94:97], v[242:245], v[202:205], v[94:97]
	v_mfma_f32_16x16x32_bf16 v[90:93], v[234:237], v[210:213], v[90:93]
	v_mfma_f32_16x16x32_bf16 v[86:89], v[242:245], v[210:213], v[86:89]
	v_mfma_f32_16x16x32_bf16 v[82:85], v[234:237], v[218:221], v[82:85]
	v_mfma_f32_16x16x32_bf16 v[78:81], v[242:245], v[218:221], v[78:81]
	v_mfma_f32_16x16x32_bf16 v[74:77], v[234:237], v[226:229], v[74:77]
	v_mfma_f32_16x16x32_bf16 v[70:73], v[242:245], v[226:229], v[70:73]
	s_mov_b32 m0, s55
	v_lshl_add_u64 v[248:249], s[44:45], 0, v[148:149]
	s_barrier
	ds_read_b128 v[198:201], v183 offset:16384
	ds_read_b128 v[202:205], v183 offset:17408
	ds_read_b128 v[206:209], v183 offset:18432
	ds_read_b128 v[210:213], v183 offset:19456
	ds_read_b128 v[214:217], v183 offset:20480
	ds_read_b128 v[218:221], v183 offset:21504
	ds_read_b128 v[222:225], v183 offset:22528
	ds_read_b128 v[226:229], v183 offset:23552
	global_load_lds_dwordx4 v[248:249], off
	v_lshl_add_u64 v[250:251], s[44:45], 0, v[152:153]
	s_mov_b32 m0, s56
	s_nop 0
	global_load_lds_dwordx4 v[250:251], off
	s_barrier
	s_waitcnt lgkmcnt(0)
	s_waitcnt lgkmcnt(0)
	v_mfma_f32_16x16x32_bf16 v[66:69], v[162:165], v[198:201], v[66:69]
	v_mfma_f32_16x16x32_bf16 v[62:65], v[190:193], v[198:201], v[62:65]
	v_mfma_f32_16x16x32_bf16 v[58:61], v[162:165], v[206:209], v[58:61]
	v_mfma_f32_16x16x32_bf16 v[54:57], v[190:193], v[206:209], v[54:57]
	v_mfma_f32_16x16x32_bf16 v[50:53], v[162:165], v[214:217], v[50:53]
	v_mfma_f32_16x16x32_bf16 v[46:49], v[190:193], v[214:217], v[46:49]
	v_mfma_f32_16x16x32_bf16 v[42:45], v[162:165], v[222:225], v[42:45]
	v_mfma_f32_16x16x32_bf16 v[38:41], v[190:193], v[222:225], v[38:41]
	v_mfma_f32_16x16x32_bf16 v[66:69], v[186:189], v[202:205], v[66:69]
	v_mfma_f32_16x16x32_bf16 v[62:65], v[194:197], v[202:205], v[62:65]
	v_mfma_f32_16x16x32_bf16 v[58:61], v[186:189], v[210:213], v[58:61]
	v_mfma_f32_16x16x32_bf16 v[54:57], v[194:197], v[210:213], v[54:57]
	v_mfma_f32_16x16x32_bf16 v[50:53], v[186:189], v[218:221], v[50:53]
	v_mfma_f32_16x16x32_bf16 v[46:49], v[194:197], v[218:221], v[46:49]
	v_mfma_f32_16x16x32_bf16 v[42:45], v[186:189], v[226:229], v[42:45]
	v_mfma_f32_16x16x32_bf16 v[38:41], v[194:197], v[226:229], v[38:41]
	s_barrier
	s_add_u32 s46, s46, s12
	s_addc_u32 s47, s47, s13
	s_add_i32 s73, s66, s54
	v_lshl_add_u64 v[252:253], s[46:47], 0, v[150:151]
	s_mov_b32 m0, s73
	v_lshl_add_u64 v[146:147], s[46:47], 0, v[154:155]
	global_load_lds_dwordx4 v[252:253], off
	s_add_i32 m0, s73, 0x2000
	s_nop 0
	global_load_lds_dwordx4 v[146:147], off
	s_waitcnt vmcnt(6)
	s_barrier
	v_mfma_f32_16x16x32_bf16 v[34:37], v[230:233], v[198:201], v[34:37]
	v_mfma_f32_16x16x32_bf16 v[30:33], v[238:241], v[198:201], v[30:33]
	v_mfma_f32_16x16x32_bf16 v[26:29], v[230:233], v[206:209], v[26:29]
	v_mfma_f32_16x16x32_bf16 v[22:25], v[238:241], v[206:209], v[22:25]
	v_mfma_f32_16x16x32_bf16 v[18:21], v[230:233], v[214:217], v[18:21]
	v_mfma_f32_16x16x32_bf16 v[14:17], v[238:241], v[214:217], v[14:17]
	v_mfma_f32_16x16x32_bf16 v[10:13], v[230:233], v[222:225], v[10:13]
	v_mfma_f32_16x16x32_bf16 v[6:9], v[238:241], v[222:225], v[6:9]
	v_mfma_f32_16x16x32_bf16 v[34:37], v[234:237], v[202:205], v[34:37]
	v_mfma_f32_16x16x32_bf16 v[30:33], v[242:245], v[202:205], v[30:33]
	v_mfma_f32_16x16x32_bf16 v[26:29], v[234:237], v[210:213], v[26:29]
	v_mfma_f32_16x16x32_bf16 v[22:25], v[242:245], v[210:213], v[22:25]
	v_mfma_f32_16x16x32_bf16 v[18:21], v[234:237], v[218:221], v[18:21]
	v_mfma_f32_16x16x32_bf16 v[14:17], v[242:245], v[218:221], v[14:17]
	v_mfma_f32_16x16x32_bf16 v[10:13], v[234:237], v[226:229], v[10:13]
	v_mfma_f32_16x16x32_bf16 v[6:9], v[242:245], v[226:229], v[6:9]
	s_add_i32 s46, 0, 0x18000
	v_add_u32_e32 v3, s46, v181
	s_barrier
	ds_read_b128 v[162:165], v3
	ds_read_b128 v[186:189], v3 offset:1024
	ds_read_b128 v[190:193], v3 offset:2048
	ds_read_b128 v[194:197], v3 offset:3072
	s_add_u32 s44, s44, 0x1d0000
	s_addc_u32 s45, s45, 0
	s_mov_b32 m0, s57
	v_lshl_add_u64 v[230:231], s[44:45], 0, v[148:149]
	ds_read_b128 v[198:201], v183 offset:32768
	ds_read_b128 v[202:205], v183 offset:33792
	ds_read_b128 v[206:209], v183 offset:34816
	ds_read_b128 v[210:213], v183 offset:35840
	ds_read_b128 v[214:217], v183 offset:36864
	ds_read_b128 v[218:221], v183 offset:37888
	ds_read_b128 v[222:225], v183 offset:38912
	ds_read_b128 v[226:229], v183 offset:39936
	global_load_lds_dwordx4 v[230:231], off
	v_lshl_add_u64 v[230:231], s[44:45], 0, v[152:153]
	s_mov_b32 m0, s58
	s_nop 0
	global_load_lds_dwordx4 v[230:231], off
	s_waitcnt lgkmcnt(8)
	s_barrier
	s_waitcnt lgkmcnt(0)
	s_waitcnt lgkmcnt(0)
	v_mfma_f32_16x16x32_bf16 v[130:133], v[162:165], v[198:201], v[130:133]
	v_mfma_f32_16x16x32_bf16 v[126:129], v[190:193], v[198:201], v[126:129]
	v_mfma_f32_16x16x32_bf16 v[122:125], v[162:165], v[206:209], v[122:125]
	v_mfma_f32_16x16x32_bf16 v[118:121], v[190:193], v[206:209], v[118:121]
	v_mfma_f32_16x16x32_bf16 v[114:117], v[162:165], v[214:217], v[114:117]
	v_mfma_f32_16x16x32_bf16 v[110:113], v[190:193], v[214:217], v[110:113]
	v_mfma_f32_16x16x32_bf16 v[106:109], v[162:165], v[222:225], v[106:109]
	v_mfma_f32_16x16x32_bf16 v[98:101], v[190:193], v[222:225], v[98:101]
	v_mfma_f32_16x16x32_bf16 v[130:133], v[186:189], v[202:205], v[130:133]
	v_mfma_f32_16x16x32_bf16 v[126:129], v[194:197], v[202:205], v[126:129]
	v_mfma_f32_16x16x32_bf16 v[122:125], v[186:189], v[210:213], v[122:125]
	v_mfma_f32_16x16x32_bf16 v[118:121], v[194:197], v[210:213], v[118:121]
	v_mfma_f32_16x16x32_bf16 v[114:117], v[186:189], v[218:221], v[114:117]
	v_mfma_f32_16x16x32_bf16 v[110:113], v[194:197], v[218:221], v[110:113]
	v_mfma_f32_16x16x32_bf16 v[106:109], v[186:189], v[226:229], v[106:109]
	v_mfma_f32_16x16x32_bf16 v[98:101], v[194:197], v[226:229], v[98:101]
	s_barrier
	s_add_i32 s44, 0, 0x1c000
	s_add_i32 s45, s46, s54
	v_add_u32_e32 v3, s44, v181
	v_lshl_add_u64 v[166:167], v[166:167], 0, s[24:25]
	s_mov_b32 m0, s45
	ds_read_b128 v[230:233], v3
	ds_read_b128 v[234:237], v3 offset:1024
	ds_read_b128 v[238:241], v3 offset:2048
	ds_read_b128 v[242:245], v3 offset:3072
	global_load_lds_dwordx4 v[166:167], off
	v_lshl_add_u64 v[166:167], v[246:247], 0, s[24:25]
	s_add_i32 m0, s45, 0x2000
	s_nop 0
	global_load_lds_dwordx4 v[166:167], off
	s_barrier
	s_waitcnt lgkmcnt(0)
	s_waitcnt lgkmcnt(0)
	v_mfma_f32_16x16x32_bf16 v[102:105], v[230:233], v[198:201], v[102:105]
	v_mfma_f32_16x16x32_bf16 v[94:97], v[238:241], v[198:201], v[94:97]
	v_mfma_f32_16x16x32_bf16 v[90:93], v[230:233], v[206:209], v[90:93]
	v_mfma_f32_16x16x32_bf16 v[86:89], v[238:241], v[206:209], v[86:89]
	v_mfma_f32_16x16x32_bf16 v[82:85], v[230:233], v[214:217], v[82:85]
	v_mfma_f32_16x16x32_bf16 v[78:81], v[238:241], v[214:217], v[78:81]
	v_mfma_f32_16x16x32_bf16 v[74:77], v[230:233], v[222:225], v[74:77]
	v_mfma_f32_16x16x32_bf16 v[70:73], v[238:241], v[222:225], v[70:73]
	v_mfma_f32_16x16x32_bf16 v[102:105], v[234:237], v[202:205], v[102:105]
	v_mfma_f32_16x16x32_bf16 v[94:97], v[242:245], v[202:205], v[94:97]
	v_mfma_f32_16x16x32_bf16 v[90:93], v[234:237], v[210:213], v[90:93]
	v_mfma_f32_16x16x32_bf16 v[86:89], v[242:245], v[210:213], v[86:89]
	v_mfma_f32_16x16x32_bf16 v[82:85], v[234:237], v[218:221], v[82:85]
	v_mfma_f32_16x16x32_bf16 v[78:81], v[242:245], v[218:221], v[78:81]
	v_mfma_f32_16x16x32_bf16 v[74:77], v[234:237], v[226:229], v[74:77]
	v_mfma_f32_16x16x32_bf16 v[70:73], v[242:245], v[226:229], v[70:73]
	s_mov_b32 m0, s61
	v_lshl_add_u64 v[166:167], v[248:249], 0, s[24:25]
	s_barrier
	ds_read_b128 v[198:201], v183 offset:49152
	ds_read_b128 v[202:205], v183 offset:50176
	ds_read_b128 v[206:209], v183 offset:51200
	ds_read_b128 v[210:213], v183 offset:52224
	ds_read_b128 v[214:217], v183 offset:53248
	ds_read_b128 v[218:221], v183 offset:54272
	ds_read_b128 v[222:225], v183 offset:55296
	ds_read_b128 v[226:229], v183 offset:56320
	global_load_lds_dwordx4 v[166:167], off
	v_lshl_add_u64 v[166:167], v[250:251], 0, s[24:25]
	s_mov_b32 m0, s62
	s_nop 0
	global_load_lds_dwordx4 v[166:167], off
	s_barrier
	s_waitcnt lgkmcnt(0)
	s_waitcnt lgkmcnt(0)
	v_mfma_f32_16x16x32_bf16 v[66:69], v[162:165], v[198:201], v[66:69]
	v_mfma_f32_16x16x32_bf16 v[62:65], v[190:193], v[198:201], v[62:65]
	v_mfma_f32_16x16x32_bf16 v[58:61], v[162:165], v[206:209], v[58:61]
	v_mfma_f32_16x16x32_bf16 v[54:57], v[190:193], v[206:209], v[54:57]
	v_mfma_f32_16x16x32_bf16 v[50:53], v[162:165], v[214:217], v[50:53]
	v_mfma_f32_16x16x32_bf16 v[46:49], v[190:193], v[214:217], v[46:49]
	v_mfma_f32_16x16x32_bf16 v[42:45], v[162:165], v[222:225], v[42:45]
	v_mfma_f32_16x16x32_bf16 v[38:41], v[190:193], v[222:225], v[38:41]
	v_mfma_f32_16x16x32_bf16 v[66:69], v[186:189], v[202:205], v[66:69]
	v_mfma_f32_16x16x32_bf16 v[62:65], v[194:197], v[202:205], v[62:65]
	v_mfma_f32_16x16x32_bf16 v[58:61], v[186:189], v[210:213], v[58:61]
	v_mfma_f32_16x16x32_bf16 v[54:57], v[194:197], v[210:213], v[54:57]
	v_mfma_f32_16x16x32_bf16 v[50:53], v[186:189], v[218:221], v[50:53]
	v_mfma_f32_16x16x32_bf16 v[46:49], v[194:197], v[218:221], v[46:49]
	v_mfma_f32_16x16x32_bf16 v[42:45], v[186:189], v[226:229], v[42:45]
	v_mfma_f32_16x16x32_bf16 v[38:41], v[194:197], v[226:229], v[38:41]
	s_barrier
	s_add_i32 s44, s44, s54
	v_lshl_add_u64 v[162:163], v[252:253], 0, s[24:25]
	s_mov_b32 m0, s44
	v_lshl_add_u64 v[146:147], v[146:147], 0, s[24:25]
	global_load_lds_dwordx4 v[162:163], off
	s_add_i32 m0, s44, 0x2000
	s_nop 0
	global_load_lds_dwordx4 v[146:147], off
	s_waitcnt vmcnt(6)
	s_barrier
	v_mfma_f32_16x16x32_bf16 v[34:37], v[230:233], v[198:201], v[34:37]
	v_mfma_f32_16x16x32_bf16 v[30:33], v[238:241], v[198:201], v[30:33]
	v_mfma_f32_16x16x32_bf16 v[26:29], v[230:233], v[206:209], v[26:29]
	v_mfma_f32_16x16x32_bf16 v[22:25], v[238:241], v[206:209], v[22:25]
	v_mfma_f32_16x16x32_bf16 v[18:21], v[230:233], v[214:217], v[18:21]
	v_mfma_f32_16x16x32_bf16 v[14:17], v[238:241], v[214:217], v[14:17]
	v_mfma_f32_16x16x32_bf16 v[10:13], v[230:233], v[222:225], v[10:13]
	v_mfma_f32_16x16x32_bf16 v[6:9], v[238:241], v[222:225], v[6:9]
	v_mfma_f32_16x16x32_bf16 v[34:37], v[234:237], v[202:205], v[34:37]
	v_mfma_f32_16x16x32_bf16 v[30:33], v[242:245], v[202:205], v[30:33]
	v_mfma_f32_16x16x32_bf16 v[26:29], v[234:237], v[210:213], v[26:29]
	v_mfma_f32_16x16x32_bf16 v[22:25], v[242:245], v[210:213], v[22:25]
	v_mfma_f32_16x16x32_bf16 v[18:21], v[234:237], v[218:221], v[18:21]
	v_mfma_f32_16x16x32_bf16 v[14:17], v[242:245], v[218:221], v[14:17]
	v_mfma_f32_16x16x32_bf16 v[10:13], v[234:237], v[226:229], v[10:13]
	v_mfma_f32_16x16x32_bf16 v[6:9], v[242:245], v[226:229], v[6:9]
	s_add_u32 s40, s40, 0x100
	s_addc_u32 s41, s41, 0
	s_andn2_b64 s[38:39], s[38:39], exec
	s_and_b64 s[44:45], s[42:43], exec
	s_or_b64 s[38:39], s[38:39], s[44:45]
	s_cmp_ge_i32 s72, s59
	s_mov_b32 s46, s72
	s_barrier
	s_cbranch_scc1 .LBB0_1484

.LBB0_1510:
	s_or_b64 exec, exec, s[40:41]
	s_add_i32 s72, s42, 2
	s_add_u32 s40, s14, s6
	v_add_u32_e32 v3, s60, v165
	s_addc_u32 s41, s15, s7
	ds_read_b128 v[168:171], v3
	ds_read_b128 v[172:175], v3 offset:1024
	ds_read_b128 v[176:179], v3 offset:2048
	ds_read_b128 v[180:183], v3 offset:3072
	s_add_u32 s40, s40, 0x100
	s_addc_u32 s41, s41, 0
	s_add_u32 s73, s70, s6
	s_addc_u32 s43, s71, s7
	s_cmp_eq_u32 s59, s42
	s_cselect_b32 s42, s30, s73
	s_cselect_b32 s41, s29, s41
	s_cselect_b32 s40, s69, s40
	s_cselect_b32 s43, s31, s43
	v_lshl_add_u64 v[216:217], v[160:161], 0, s[6:7]
	s_add_i32 m0, s50, 0xc000
	ds_read_b128 v[184:187], v1
	ds_read_b128 v[188:191], v1 offset:1024
	ds_read_b128 v[192:195], v1 offset:2048
	ds_read_b128 v[196:199], v1 offset:3072
	ds_read_b128 v[200:203], v1 offset:4096
	ds_read_b128 v[204:207], v1 offset:5120
	ds_read_b128 v[208:211], v1 offset:6144
	ds_read_b128 v[212:215], v1 offset:7168
	global_load_lds_dwordx4 v[216:217], off
	v_lshl_add_u64 v[216:217], v[162:163], 0, s[6:7]
	s_add_i32 m0, s50, 0xe000
	s_nop 0
	global_load_lds_dwordx4 v[216:217], off
	s_waitcnt lgkmcnt(8)
	s_barrier
	s_waitcnt lgkmcnt(0)
	s_waitcnt lgkmcnt(0)
	v_mfma_f32_16x16x32_bf16 v[130:133], v[168:171], v[184:187], v[130:133]
	v_mfma_f32_16x16x32_bf16 v[126:129], v[176:179], v[184:187], v[126:129]
	v_mfma_f32_16x16x32_bf16 v[122:125], v[168:171], v[192:195], v[122:125]
	v_mfma_f32_16x16x32_bf16 v[118:121], v[176:179], v[192:195], v[118:121]
	v_mfma_f32_16x16x32_bf16 v[114:117], v[168:171], v[200:203], v[114:117]
	v_mfma_f32_16x16x32_bf16 v[110:113], v[176:179], v[200:203], v[110:113]
	v_mfma_f32_16x16x32_bf16 v[106:109], v[168:171], v[208:211], v[106:109]
	v_mfma_f32_16x16x32_bf16 v[98:101], v[176:179], v[208:211], v[98:101]
	v_mfma_f32_16x16x32_bf16 v[130:133], v[172:175], v[188:191], v[130:133]
	v_mfma_f32_16x16x32_bf16 v[126:129], v[180:183], v[188:191], v[126:129]
	v_mfma_f32_16x16x32_bf16 v[122:125], v[172:175], v[196:199], v[122:125]
	v_mfma_f32_16x16x32_bf16 v[118:121], v[180:183], v[196:199], v[118:121]
	v_mfma_f32_16x16x32_bf16 v[114:117], v[172:175], v[204:207], v[114:117]
	v_mfma_f32_16x16x32_bf16 v[110:113], v[180:183], v[204:207], v[110:113]
	v_mfma_f32_16x16x32_bf16 v[106:109], v[172:175], v[212:215], v[106:109]
	v_mfma_f32_16x16x32_bf16 v[98:101], v[180:183], v[212:215], v[98:101]
	s_barrier
	s_add_i32 s73, s60, s49
	v_add_u32_e32 v3, s61, v165
	v_lshl_add_u64 v[232:233], s[42:43], 0, v[136:137]
	s_mov_b32 m0, s73
	ds_read_b128 v[216:219], v3
	ds_read_b128 v[220:223], v3 offset:1024
	ds_read_b128 v[224:227], v3 offset:2048
	ds_read_b128 v[228:231], v3 offset:3072
	global_load_lds_dwordx4 v[232:233], off
	v_lshl_add_u64 v[234:235], s[42:43], 0, v[140:141]
	s_add_i32 m0, s73, 0x2000
	s_nop 0
	global_load_lds_dwordx4 v[234:235], off
	s_barrier
	s_waitcnt lgkmcnt(0)
	s_waitcnt lgkmcnt(0)
	v_mfma_f32_16x16x32_bf16 v[102:105], v[216:219], v[184:187], v[102:105]
	v_mfma_f32_16x16x32_bf16 v[94:97], v[224:227], v[184:187], v[94:97]
	v_mfma_f32_16x16x32_bf16 v[90:93], v[216:219], v[192:195], v[90:93]
	v_mfma_f32_16x16x32_bf16 v[86:89], v[224:227], v[192:195], v[86:89]
	v_mfma_f32_16x16x32_bf16 v[82:85], v[216:219], v[200:203], v[82:85]
	v_mfma_f32_16x16x32_bf16 v[78:81], v[224:227], v[200:203], v[78:81]
	v_mfma_f32_16x16x32_bf16 v[74:77], v[216:219], v[208:211], v[74:77]
	v_mfma_f32_16x16x32_bf16 v[70:73], v[224:227], v[208:211], v[70:73]
	v_mfma_f32_16x16x32_bf16 v[102:105], v[220:223], v[188:191], v[102:105]
	v_mfma_f32_16x16x32_bf16 v[94:97], v[228:231], v[188:191], v[94:97]
	v_mfma_f32_16x16x32_bf16 v[90:93], v[220:223], v[196:199], v[90:93]
	v_mfma_f32_16x16x32_bf16 v[86:89], v[228:231], v[196:199], v[86:89]
	v_mfma_f32_16x16x32_bf16 v[82:85], v[220:223], v[204:207], v[82:85]
	v_mfma_f32_16x16x32_bf16 v[78:81], v[228:231], v[204:207], v[78:81]
	v_mfma_f32_16x16x32_bf16 v[74:77], v[220:223], v[212:215], v[74:77]
	v_mfma_f32_16x16x32_bf16 v[70:73], v[228:231], v[212:215], v[70:73]
	s_mov_b32 m0, s50
	v_lshl_add_u64 v[236:237], s[40:41], 0, v[134:135]
	s_barrier
	ds_read_b128 v[184:187], v1 offset:16384
	ds_read_b128 v[188:191], v1 offset:17408
	ds_read_b128 v[192:195], v1 offset:18432
	ds_read_b128 v[196:199], v1 offset:19456
	ds_read_b128 v[200:203], v1 offset:20480
	ds_read_b128 v[204:207], v1 offset:21504
	ds_read_b128 v[208:211], v1 offset:22528
	ds_read_b128 v[212:215], v1 offset:23552
	global_load_lds_dwordx4 v[236:237], off
	v_lshl_add_u64 v[238:239], s[40:41], 0, v[138:139]
	s_mov_b32 m0, s51
	s_nop 0
	global_load_lds_dwordx4 v[238:239], off
	s_barrier
	s_waitcnt lgkmcnt(0)
	s_waitcnt lgkmcnt(0)
	v_mfma_f32_16x16x32_bf16 v[66:69], v[168:171], v[184:187], v[66:69]
	v_mfma_f32_16x16x32_bf16 v[62:65], v[176:179], v[184:187], v[62:65]
	v_mfma_f32_16x16x32_bf16 v[58:61], v[168:171], v[192:195], v[58:61]
	v_mfma_f32_16x16x32_bf16 v[54:57], v[176:179], v[192:195], v[54:57]
	v_mfma_f32_16x16x32_bf16 v[50:53], v[168:171], v[200:203], v[50:53]
	v_mfma_f32_16x16x32_bf16 v[46:49], v[176:179], v[200:203], v[46:49]
	v_mfma_f32_16x16x32_bf16 v[42:45], v[168:171], v[208:211], v[42:45]
	v_mfma_f32_16x16x32_bf16 v[38:41], v[176:179], v[208:211], v[38:41]
	v_mfma_f32_16x16x32_bf16 v[66:69], v[172:175], v[188:191], v[66:69]
	v_mfma_f32_16x16x32_bf16 v[62:65], v[180:183], v[188:191], v[62:65]
	v_mfma_f32_16x16x32_bf16 v[58:61], v[172:175], v[196:199], v[58:61]
	v_mfma_f32_16x16x32_bf16 v[54:57], v[180:183], v[196:199], v[54:57]
	v_mfma_f32_16x16x32_bf16 v[50:53], v[172:175], v[204:207], v[50:53]
	v_mfma_f32_16x16x32_bf16 v[46:49], v[180:183], v[204:207], v[46:49]
	v_mfma_f32_16x16x32_bf16 v[42:45], v[172:175], v[212:215], v[42:45]
	v_mfma_f32_16x16x32_bf16 v[38:41], v[180:183], v[212:215], v[38:41]
	s_barrier
	s_add_u32 s42, s42, s0
	s_addc_u32 s43, s43, s1
	s_add_i32 s73, s61, s49
	v_lshl_add_u64 v[240:241], s[42:43], 0, v[136:137]
	s_mov_b32 m0, s73
	v_lshl_add_u64 v[242:243], s[42:43], 0, v[140:141]
	global_load_lds_dwordx4 v[240:241], off
	s_add_i32 m0, s73, 0x2000
	s_nop 0
	global_load_lds_dwordx4 v[242:243], off
	s_waitcnt vmcnt(6)
	s_barrier
	v_mfma_f32_16x16x32_bf16 v[34:37], v[216:219], v[184:187], v[34:37]
	v_mfma_f32_16x16x32_bf16 v[30:33], v[224:227], v[184:187], v[30:33]
	v_mfma_f32_16x16x32_bf16 v[26:29], v[216:219], v[192:195], v[26:29]
	v_mfma_f32_16x16x32_bf16 v[22:25], v[224:227], v[192:195], v[22:25]
	v_mfma_f32_16x16x32_bf16 v[18:21], v[216:219], v[200:203], v[18:21]
	v_mfma_f32_16x16x32_bf16 v[14:17], v[224:227], v[200:203], v[14:17]
	v_mfma_f32_16x16x32_bf16 v[10:13], v[216:219], v[208:211], v[10:13]
	v_mfma_f32_16x16x32_bf16 v[6:9], v[224:227], v[208:211], v[6:9]
	v_mfma_f32_16x16x32_bf16 v[34:37], v[220:223], v[188:191], v[34:37]
	v_mfma_f32_16x16x32_bf16 v[30:33], v[228:231], v[188:191], v[30:33]
	v_mfma_f32_16x16x32_bf16 v[26:29], v[220:223], v[196:199], v[26:29]
	v_mfma_f32_16x16x32_bf16 v[22:25], v[228:231], v[196:199], v[22:25]
	v_mfma_f32_16x16x32_bf16 v[18:21], v[220:223], v[204:207], v[18:21]
	v_mfma_f32_16x16x32_bf16 v[14:17], v[228:231], v[204:207], v[14:17]
	v_mfma_f32_16x16x32_bf16 v[10:13], v[220:223], v[212:215], v[10:13]
	v_mfma_f32_16x16x32_bf16 v[6:9], v[228:231], v[212:215], v[6:9]
	s_add_i32 s42, 0, 0x18000
	v_add_u32_e32 v3, s42, v165
	s_barrier
	ds_read_b128 v[168:171], v3
	ds_read_b128 v[172:175], v3 offset:1024
	ds_read_b128 v[176:179], v3 offset:2048
	ds_read_b128 v[180:183], v3 offset:3072
	s_add_u32 s40, s40, 0x10000
	s_addc_u32 s41, s41, 0
	s_mov_b32 m0, s52
	v_lshl_add_u64 v[216:217], s[40:41], 0, v[134:135]
	ds_read_b128 v[184:187], v1 offset:32768
	ds_read_b128 v[188:191], v1 offset:33792
	ds_read_b128 v[192:195], v1 offset:34816
	ds_read_b128 v[196:199], v1 offset:35840
	ds_read_b128 v[200:203], v1 offset:36864
	ds_read_b128 v[204:207], v1 offset:37888
	ds_read_b128 v[208:211], v1 offset:38912
	ds_read_b128 v[212:215], v1 offset:39936
	global_load_lds_dwordx4 v[216:217], off
	v_lshl_add_u64 v[216:217], s[40:41], 0, v[138:139]
	s_mov_b32 m0, s53
	s_nop 0
	global_load_lds_dwordx4 v[216:217], off
	s_waitcnt lgkmcnt(8)
	s_barrier
	s_waitcnt lgkmcnt(0)
	s_waitcnt lgkmcnt(0)
	v_mfma_f32_16x16x32_bf16 v[130:133], v[168:171], v[184:187], v[130:133]
	v_mfma_f32_16x16x32_bf16 v[126:129], v[176:179], v[184:187], v[126:129]
	v_mfma_f32_16x16x32_bf16 v[122:125], v[168:171], v[192:195], v[122:125]
	v_mfma_f32_16x16x32_bf16 v[118:121], v[176:179], v[192:195], v[118:121]
	v_mfma_f32_16x16x32_bf16 v[114:117], v[168:171], v[200:203], v[114:117]
	v_mfma_f32_16x16x32_bf16 v[110:113], v[176:179], v[200:203], v[110:113]
	v_mfma_f32_16x16x32_bf16 v[106:109], v[168:171], v[208:211], v[106:109]
	v_mfma_f32_16x16x32_bf16 v[98:101], v[176:179], v[208:211], v[98:101]
	v_mfma_f32_16x16x32_bf16 v[130:133], v[172:175], v[188:191], v[130:133]
	v_mfma_f32_16x16x32_bf16 v[126:129], v[180:183], v[188:191], v[126:129]
	v_mfma_f32_16x16x32_bf16 v[122:125], v[172:175], v[196:199], v[122:125]
	v_mfma_f32_16x16x32_bf16 v[118:121], v[180:183], v[196:199], v[118:121]
	v_mfma_f32_16x16x32_bf16 v[114:117], v[172:175], v[204:207], v[114:117]
	v_mfma_f32_16x16x32_bf16 v[110:113], v[180:183], v[204:207], v[110:113]
	v_mfma_f32_16x16x32_bf16 v[106:109], v[172:175], v[212:215], v[106:109]
	v_mfma_f32_16x16x32_bf16 v[98:101], v[180:183], v[212:215], v[98:101]
	s_barrier
	s_add_i32 s40, 0, 0x1c000
	s_add_i32 s41, s42, s49
	v_add_u32_e32 v3, s40, v165
	v_lshl_add_u64 v[232:233], v[232:233], 0, s[16:17]
	s_mov_b32 m0, s41
	ds_read_b128 v[216:219], v3
	ds_read_b128 v[220:223], v3 offset:1024
	ds_read_b128 v[224:227], v3 offset:2048
	ds_read_b128 v[228:231], v3 offset:3072
	global_load_lds_dwordx4 v[232:233], off
	v_lshl_add_u64 v[232:233], v[234:235], 0, s[16:17]
	s_add_i32 m0, s41, 0x2000
	s_nop 0
	global_load_lds_dwordx4 v[232:233], off
	s_barrier
	s_waitcnt lgkmcnt(0)
	s_waitcnt lgkmcnt(0)
	v_mfma_f32_16x16x32_bf16 v[102:105], v[216:219], v[184:187], v[102:105]
	v_mfma_f32_16x16x32_bf16 v[94:97], v[224:227], v[184:187], v[94:97]
	v_mfma_f32_16x16x32_bf16 v[90:93], v[216:219], v[192:195], v[90:93]
	v_mfma_f32_16x16x32_bf16 v[86:89], v[224:227], v[192:195], v[86:89]
	v_mfma_f32_16x16x32_bf16 v[82:85], v[216:219], v[200:203], v[82:85]
	v_mfma_f32_16x16x32_bf16 v[78:81], v[224:227], v[200:203], v[78:81]
	v_mfma_f32_16x16x32_bf16 v[74:77], v[216:219], v[208:211], v[74:77]
	v_mfma_f32_16x16x32_bf16 v[70:73], v[224:227], v[208:211], v[70:73]
	v_mfma_f32_16x16x32_bf16 v[102:105], v[220:223], v[188:191], v[102:105]
	v_mfma_f32_16x16x32_bf16 v[94:97], v[228:231], v[188:191], v[94:97]
	v_mfma_f32_16x16x32_bf16 v[90:93], v[220:223], v[196:199], v[90:93]
	v_mfma_f32_16x16x32_bf16 v[86:89], v[228:231], v[196:199], v[86:89]
	v_mfma_f32_16x16x32_bf16 v[82:85], v[220:223], v[204:207], v[82:85]
	v_mfma_f32_16x16x32_bf16 v[78:81], v[228:231], v[204:207], v[78:81]
	v_mfma_f32_16x16x32_bf16 v[74:77], v[220:223], v[212:215], v[74:77]
	v_mfma_f32_16x16x32_bf16 v[70:73], v[228:231], v[212:215], v[70:73]
	s_mov_b32 m0, s56
	v_lshl_add_u64 v[232:233], v[236:237], 0, s[16:17]
	s_barrier
	ds_read_b128 v[184:187], v1 offset:49152
	ds_read_b128 v[188:191], v1 offset:50176
	ds_read_b128 v[192:195], v1 offset:51200
	ds_read_b128 v[196:199], v1 offset:52224
	ds_read_b128 v[200:203], v1 offset:53248
	ds_read_b128 v[204:207], v1 offset:54272
	ds_read_b128 v[208:211], v1 offset:55296
	ds_read_b128 v[212:215], v1 offset:56320
	global_load_lds_dwordx4 v[232:233], off
	v_lshl_add_u64 v[232:233], v[238:239], 0, s[16:17]
	s_mov_b32 m0, s57
	s_nop 0
	global_load_lds_dwordx4 v[232:233], off
	s_barrier
	s_waitcnt lgkmcnt(0)
	s_waitcnt lgkmcnt(0)
	v_mfma_f32_16x16x32_bf16 v[66:69], v[168:171], v[184:187], v[66:69]
	v_mfma_f32_16x16x32_bf16 v[62:65], v[176:179], v[184:187], v[62:65]
	v_mfma_f32_16x16x32_bf16 v[58:61], v[168:171], v[192:195], v[58:61]
	v_mfma_f32_16x16x32_bf16 v[54:57], v[176:179], v[192:195], v[54:57]
	v_mfma_f32_16x16x32_bf16 v[50:53], v[168:171], v[200:203], v[50:53]
	v_mfma_f32_16x16x32_bf16 v[46:49], v[176:179], v[200:203], v[46:49]
	v_mfma_f32_16x16x32_bf16 v[42:45], v[168:171], v[208:211], v[42:45]
	v_mfma_f32_16x16x32_bf16 v[38:41], v[176:179], v[208:211], v[38:41]
	v_mfma_f32_16x16x32_bf16 v[66:69], v[172:175], v[188:191], v[66:69]
	v_mfma_f32_16x16x32_bf16 v[62:65], v[180:183], v[188:191], v[62:65]
	v_mfma_f32_16x16x32_bf16 v[58:61], v[172:175], v[196:199], v[58:61]
	v_mfma_f32_16x16x32_bf16 v[54:57], v[180:183], v[196:199], v[54:57]
	v_mfma_f32_16x16x32_bf16 v[50:53], v[172:175], v[204:207], v[50:53]
	v_mfma_f32_16x16x32_bf16 v[46:49], v[180:183], v[204:207], v[46:49]
	v_mfma_f32_16x16x32_bf16 v[42:45], v[172:175], v[212:215], v[42:45]
	v_mfma_f32_16x16x32_bf16 v[38:41], v[180:183], v[212:215], v[38:41]
	s_barrier
	s_add_i32 s40, s40, s49
	v_lshl_add_u64 v[168:169], v[240:241], 0, s[16:17]
	s_mov_b32 m0, s40
	s_nop 0
	global_load_lds_dwordx4 v[168:169], off
	v_lshl_add_u64 v[168:169], v[242:243], 0, s[16:17]
	s_add_i32 m0, s40, 0x2000
	s_nop 0
	global_load_lds_dwordx4 v[168:169], off
	s_waitcnt vmcnt(6)
	s_barrier
	v_mfma_f32_16x16x32_bf16 v[34:37], v[216:219], v[184:187], v[34:37]
	v_mfma_f32_16x16x32_bf16 v[30:33], v[224:227], v[184:187], v[30:33]
	v_mfma_f32_16x16x32_bf16 v[26:29], v[216:219], v[192:195], v[26:29]
	v_mfma_f32_16x16x32_bf16 v[22:25], v[224:227], v[192:195], v[22:25]
	v_mfma_f32_16x16x32_bf16 v[18:21], v[216:219], v[200:203], v[18:21]
	v_mfma_f32_16x16x32_bf16 v[14:17], v[224:227], v[200:203], v[14:17]
	v_mfma_f32_16x16x32_bf16 v[10:13], v[216:219], v[208:211], v[10:13]
	v_mfma_f32_16x16x32_bf16 v[6:9], v[224:227], v[208:211], v[6:9]
	v_mfma_f32_16x16x32_bf16 v[34:37], v[220:223], v[188:191], v[34:37]
	v_mfma_f32_16x16x32_bf16 v[30:33], v[228:231], v[188:191], v[30:33]
	v_mfma_f32_16x16x32_bf16 v[26:29], v[220:223], v[196:199], v[26:29]
	v_mfma_f32_16x16x32_bf16 v[22:25], v[228:231], v[196:199], v[22:25]
	v_mfma_f32_16x16x32_bf16 v[18:21], v[220:223], v[204:207], v[18:21]
	v_mfma_f32_16x16x32_bf16 v[14:17], v[228:231], v[204:207], v[14:17]
	v_mfma_f32_16x16x32_bf16 v[10:13], v[220:223], v[212:215], v[10:13]
	v_mfma_f32_16x16x32_bf16 v[6:9], v[228:231], v[212:215], v[6:9]
	s_add_u32 s6, s6, 0x100
	s_addc_u32 s7, s7, 0
	s_andn2_b64 s[36:37], s[36:37], exec
	s_and_b64 s[40:41], s[38:39], exec
	s_or_b64 s[36:37], s[36:37], s[40:41]
	s_cmp_ge_i32 s72, s54
	s_mov_b32 s42, s72
	s_barrier
	s_cbranch_scc1 .LBB0_1513

.LBB0_1596:
	s_or_b64 exec, exec, s[10:11]
	s_add_i32 s69, s12, 2
	v_add_u32_e32 v3, s63, v228
	s_add_u32 s10, s24, s6
	ds_read_b128 v[140:143], v3
	ds_read_b128 v[144:147], v3 offset:1024
	ds_read_b128 v[148:151], v3 offset:2048
	ds_read_b128 v[152:155], v3 offset:3072
	s_addc_u32 s11, s25, s7
	s_add_u32 s10, s10, 0x100
	s_addc_u32 s11, s11, 0
	s_add_u32 s70, s46, s6
	s_addc_u32 s13, s68, s7
	s_cmp_eq_u32 s62, s12
	s_cselect_b32 s11, s33, s11
	s_cselect_b32 s10, s41, s10
	s_cselect_b32 s13, s43, s13
	s_cselect_b32 s12, s42, s70
	v_lshl_add_u64 v[164:165], v[136:137], 0, s[6:7]
	s_add_i32 m0, s53, 0xc000
	ds_read_b128 v[156:159], v230
	ds_read_b128 v[160:163], v230 offset:1024
	ds_read_b128 v[184:187], v230 offset:2048
	ds_read_b128 v[196:199], v230 offset:3072
	ds_read_b128 v[200:203], v230 offset:4096
	ds_read_b128 v[204:207], v230 offset:5120
	ds_read_b128 v[208:211], v230 offset:6144
	ds_read_b128 v[212:215], v230 offset:7168
	global_load_lds_dwordx4 v[164:165], off
	v_lshl_add_u64 v[164:165], v[138:139], 0, s[6:7]
	s_add_i32 m0, s53, 0xe000
	s_nop 0
	global_load_lds_dwordx4 v[164:165], off
	s_waitcnt lgkmcnt(8)
	s_barrier
	s_waitcnt lgkmcnt(0)
	s_waitcnt lgkmcnt(0)
	v_mfma_f32_16x16x32_bf16 v[130:133], v[140:143], v[156:159], v[130:133]
	v_mfma_f32_16x16x32_bf16 v[126:129], v[148:151], v[156:159], v[126:129]
	v_mfma_f32_16x16x32_bf16 v[122:125], v[140:143], v[184:187], v[122:125]
	v_mfma_f32_16x16x32_bf16 v[118:121], v[148:151], v[184:187], v[118:121]
	v_mfma_f32_16x16x32_bf16 v[114:117], v[140:143], v[200:203], v[114:117]
	v_mfma_f32_16x16x32_bf16 v[110:113], v[148:151], v[200:203], v[110:113]
	v_mfma_f32_16x16x32_bf16 v[106:109], v[140:143], v[208:211], v[106:109]
	v_mfma_f32_16x16x32_bf16 v[102:105], v[148:151], v[208:211], v[102:105]
	v_mfma_f32_16x16x32_bf16 v[130:133], v[144:147], v[160:163], v[130:133]
	v_mfma_f32_16x16x32_bf16 v[126:129], v[152:155], v[160:163], v[126:129]
	v_mfma_f32_16x16x32_bf16 v[122:125], v[144:147], v[196:199], v[122:125]
	v_mfma_f32_16x16x32_bf16 v[118:121], v[152:155], v[196:199], v[118:121]
	v_mfma_f32_16x16x32_bf16 v[114:117], v[144:147], v[204:207], v[114:117]
	v_mfma_f32_16x16x32_bf16 v[110:113], v[152:155], v[204:207], v[110:113]
	v_mfma_f32_16x16x32_bf16 v[106:109], v[144:147], v[212:215], v[106:109]
	v_mfma_f32_16x16x32_bf16 v[102:105], v[152:155], v[212:215], v[102:105]
	s_barrier
	s_add_i32 s70, s63, s52
	v_add_u32_e32 v3, s64, v228
	v_lshl_add_u64 v[164:165], s[12:13], 0, v[168:169]
	s_mov_b32 m0, s70
	ds_read_b128 v[216:219], v3
	ds_read_b128 v[220:223], v3 offset:1024
	ds_read_b128 v[224:227], v3 offset:2048
	ds_read_b128 v[234:237], v3 offset:3072
	global_load_lds_dwordx4 v[164:165], off
	v_lshl_add_u64 v[188:189], s[12:13], 0, v[172:173]
	s_add_i32 m0, s70, 0x2000
	s_nop 0
	global_load_lds_dwordx4 v[188:189], off
	s_barrier
	s_waitcnt lgkmcnt(0)
	s_waitcnt lgkmcnt(0)
	v_mfma_f32_16x16x32_bf16 v[98:101], v[216:219], v[156:159], v[98:101]
	v_mfma_f32_16x16x32_bf16 v[94:97], v[224:227], v[156:159], v[94:97]
	v_mfma_f32_16x16x32_bf16 v[90:93], v[216:219], v[184:187], v[90:93]
	v_mfma_f32_16x16x32_bf16 v[86:89], v[224:227], v[184:187], v[86:89]
	v_mfma_f32_16x16x32_bf16 v[82:85], v[216:219], v[200:203], v[82:85]
	v_mfma_f32_16x16x32_bf16 v[78:81], v[224:227], v[200:203], v[78:81]
	v_mfma_f32_16x16x32_bf16 v[74:77], v[216:219], v[208:211], v[74:77]
	v_mfma_f32_16x16x32_bf16 v[70:73], v[224:227], v[208:211], v[70:73]
	v_mfma_f32_16x16x32_bf16 v[98:101], v[220:223], v[160:163], v[98:101]
	v_mfma_f32_16x16x32_bf16 v[94:97], v[234:237], v[160:163], v[94:97]
	v_mfma_f32_16x16x32_bf16 v[90:93], v[220:223], v[196:199], v[90:93]
	v_mfma_f32_16x16x32_bf16 v[86:89], v[234:237], v[196:199], v[86:89]
	v_mfma_f32_16x16x32_bf16 v[82:85], v[220:223], v[204:207], v[82:85]
	v_mfma_f32_16x16x32_bf16 v[78:81], v[234:237], v[204:207], v[78:81]
	v_mfma_f32_16x16x32_bf16 v[74:77], v[220:223], v[212:215], v[74:77]
	v_mfma_f32_16x16x32_bf16 v[70:73], v[234:237], v[212:215], v[70:73]
	s_mov_b32 m0, s53
	v_lshl_add_u64 v[238:239], s[10:11], 0, v[166:167]
	s_barrier
	ds_read_b128 v[156:159], v230 offset:16384
	ds_read_b128 v[160:163], v230 offset:17408
	ds_read_b128 v[184:187], v230 offset:18432
	ds_read_b128 v[196:199], v230 offset:19456
	ds_read_b128 v[200:203], v230 offset:20480
	ds_read_b128 v[204:207], v230 offset:21504
	ds_read_b128 v[208:211], v230 offset:22528
	ds_read_b128 v[212:215], v230 offset:23552
	global_load_lds_dwordx4 v[238:239], off
	v_lshl_add_u64 v[240:241], s[10:11], 0, v[170:171]
	s_mov_b32 m0, s54
	s_nop 0
	global_load_lds_dwordx4 v[240:241], off
	s_barrier
	s_waitcnt lgkmcnt(0)
	s_waitcnt lgkmcnt(0)
	v_mfma_f32_16x16x32_bf16 v[66:69], v[140:143], v[156:159], v[66:69]
	v_mfma_f32_16x16x32_bf16 v[62:65], v[148:151], v[156:159], v[62:65]
	v_mfma_f32_16x16x32_bf16 v[58:61], v[140:143], v[184:187], v[58:61]
	v_mfma_f32_16x16x32_bf16 v[54:57], v[148:151], v[184:187], v[54:57]
	v_mfma_f32_16x16x32_bf16 v[50:53], v[140:143], v[200:203], v[50:53]
	v_mfma_f32_16x16x32_bf16 v[46:49], v[148:151], v[200:203], v[46:49]
	v_mfma_f32_16x16x32_bf16 v[42:45], v[140:143], v[208:211], v[42:45]
	v_mfma_f32_16x16x32_bf16 v[38:41], v[148:151], v[208:211], v[38:41]
	v_mfma_f32_16x16x32_bf16 v[66:69], v[144:147], v[160:163], v[66:69]
	v_mfma_f32_16x16x32_bf16 v[62:65], v[152:155], v[160:163], v[62:65]
	v_mfma_f32_16x16x32_bf16 v[58:61], v[144:147], v[196:199], v[58:61]
	v_mfma_f32_16x16x32_bf16 v[54:57], v[152:155], v[196:199], v[54:57]
	v_mfma_f32_16x16x32_bf16 v[50:53], v[144:147], v[204:207], v[50:53]
	v_mfma_f32_16x16x32_bf16 v[46:49], v[152:155], v[204:207], v[46:49]
	v_mfma_f32_16x16x32_bf16 v[42:45], v[144:147], v[212:215], v[42:45]
	v_mfma_f32_16x16x32_bf16 v[38:41], v[152:155], v[212:215], v[38:41]
	s_barrier
	s_add_u32 s12, s12, s18
	s_addc_u32 s13, s13, s19
	s_add_i32 s70, s64, s52
	v_lshl_add_u64 v[242:243], s[12:13], 0, v[168:169]
	s_mov_b32 m0, s70
	v_lshl_add_u64 v[244:245], s[12:13], 0, v[172:173]
	global_load_lds_dwordx4 v[242:243], off
	s_add_i32 m0, s70, 0x2000
	s_nop 0
	global_load_lds_dwordx4 v[244:245], off
	s_waitcnt vmcnt(6)
	s_barrier
	v_mfma_f32_16x16x32_bf16 v[34:37], v[216:219], v[156:159], v[34:37]
	v_mfma_f32_16x16x32_bf16 v[30:33], v[224:227], v[156:159], v[30:33]
	v_mfma_f32_16x16x32_bf16 v[26:29], v[216:219], v[184:187], v[26:29]
	v_mfma_f32_16x16x32_bf16 v[22:25], v[224:227], v[184:187], v[22:25]
	v_mfma_f32_16x16x32_bf16 v[18:21], v[216:219], v[200:203], v[18:21]
	v_mfma_f32_16x16x32_bf16 v[14:17], v[224:227], v[200:203], v[14:17]
	v_mfma_f32_16x16x32_bf16 v[10:13], v[216:219], v[208:211], v[10:13]
	v_mfma_f32_16x16x32_bf16 v[6:9], v[224:227], v[208:211], v[6:9]
	v_mfma_f32_16x16x32_bf16 v[34:37], v[220:223], v[160:163], v[34:37]
	v_mfma_f32_16x16x32_bf16 v[30:33], v[234:237], v[160:163], v[30:33]
	v_mfma_f32_16x16x32_bf16 v[26:29], v[220:223], v[196:199], v[26:29]
	v_mfma_f32_16x16x32_bf16 v[22:25], v[234:237], v[196:199], v[22:25]
	v_mfma_f32_16x16x32_bf16 v[18:21], v[220:223], v[204:207], v[18:21]
	v_mfma_f32_16x16x32_bf16 v[14:17], v[234:237], v[204:207], v[14:17]
	v_mfma_f32_16x16x32_bf16 v[10:13], v[220:223], v[212:215], v[10:13]
	v_mfma_f32_16x16x32_bf16 v[6:9], v[234:237], v[212:215], v[6:9]
	s_add_i32 s12, 0, 0x18000
	v_add_u32_e32 v3, s12, v228
	s_barrier
	ds_read_b128 v[140:143], v3
	ds_read_b128 v[144:147], v3 offset:1024
	ds_read_b128 v[148:151], v3 offset:2048
	ds_read_b128 v[152:155], v3 offset:3072
	s_add_u32 s10, s10, 0x80000
	s_addc_u32 s11, s11, 0
	s_mov_b32 m0, s55
	v_lshl_add_u64 v[216:217], s[10:11], 0, v[166:167]
	ds_read_b128 v[156:159], v230 offset:32768
	ds_read_b128 v[160:163], v230 offset:33792
	ds_read_b128 v[184:187], v230 offset:34816
	ds_read_b128 v[196:199], v230 offset:35840
	ds_read_b128 v[200:203], v230 offset:36864
	ds_read_b128 v[204:207], v230 offset:37888
	ds_read_b128 v[208:211], v230 offset:38912
	ds_read_b128 v[212:215], v230 offset:39936
	global_load_lds_dwordx4 v[216:217], off
	v_lshl_add_u64 v[216:217], s[10:11], 0, v[170:171]
	s_mov_b32 m0, s56
	s_nop 0
	global_load_lds_dwordx4 v[216:217], off
	s_waitcnt lgkmcnt(8)
	s_barrier
	s_waitcnt lgkmcnt(0)
	s_waitcnt lgkmcnt(0)
	v_mfma_f32_16x16x32_bf16 v[130:133], v[140:143], v[156:159], v[130:133]
	v_mfma_f32_16x16x32_bf16 v[126:129], v[148:151], v[156:159], v[126:129]
	v_mfma_f32_16x16x32_bf16 v[122:125], v[140:143], v[184:187], v[122:125]
	v_mfma_f32_16x16x32_bf16 v[118:121], v[148:151], v[184:187], v[118:121]
	v_mfma_f32_16x16x32_bf16 v[114:117], v[140:143], v[200:203], v[114:117]
	v_mfma_f32_16x16x32_bf16 v[110:113], v[148:151], v[200:203], v[110:113]
	v_mfma_f32_16x16x32_bf16 v[106:109], v[140:143], v[208:211], v[106:109]
	v_mfma_f32_16x16x32_bf16 v[102:105], v[148:151], v[208:211], v[102:105]
	v_mfma_f32_16x16x32_bf16 v[130:133], v[144:147], v[160:163], v[130:133]
	v_mfma_f32_16x16x32_bf16 v[126:129], v[152:155], v[160:163], v[126:129]
	v_mfma_f32_16x16x32_bf16 v[122:125], v[144:147], v[196:199], v[122:125]
	v_mfma_f32_16x16x32_bf16 v[118:121], v[152:155], v[196:199], v[118:121]
	v_mfma_f32_16x16x32_bf16 v[114:117], v[144:147], v[204:207], v[114:117]
	v_mfma_f32_16x16x32_bf16 v[110:113], v[152:155], v[204:207], v[110:113]
	v_mfma_f32_16x16x32_bf16 v[106:109], v[144:147], v[212:215], v[106:109]
	v_mfma_f32_16x16x32_bf16 v[102:105], v[152:155], v[212:215], v[102:105]
	s_barrier
	s_add_i32 s10, 0, 0x1c000
	s_add_i32 s11, s12, s52
	v_add_u32_e32 v3, s10, v228
	v_lshl_add_u64 v[164:165], v[164:165], 0, s[36:37]
	s_mov_b32 m0, s11
	ds_read_b128 v[216:219], v3
	ds_read_b128 v[220:223], v3 offset:1024
	ds_read_b128 v[224:227], v3 offset:2048
	ds_read_b128 v[234:237], v3 offset:3072
	global_load_lds_dwordx4 v[164:165], off
	v_lshl_add_u64 v[164:165], v[188:189], 0, s[36:37]
	s_add_i32 m0, s11, 0x2000
	s_nop 0
	global_load_lds_dwordx4 v[164:165], off
	s_barrier
	s_waitcnt lgkmcnt(0)
	s_waitcnt lgkmcnt(0)
	v_mfma_f32_16x16x32_bf16 v[98:101], v[216:219], v[156:159], v[98:101]
	v_mfma_f32_16x16x32_bf16 v[94:97], v[224:227], v[156:159], v[94:97]
	v_mfma_f32_16x16x32_bf16 v[90:93], v[216:219], v[184:187], v[90:93]
	v_mfma_f32_16x16x32_bf16 v[86:89], v[224:227], v[184:187], v[86:89]
	v_mfma_f32_16x16x32_bf16 v[82:85], v[216:219], v[200:203], v[82:85]
	v_mfma_f32_16x16x32_bf16 v[78:81], v[224:227], v[200:203], v[78:81]
	v_mfma_f32_16x16x32_bf16 v[74:77], v[216:219], v[208:211], v[74:77]
	v_mfma_f32_16x16x32_bf16 v[70:73], v[224:227], v[208:211], v[70:73]
	v_mfma_f32_16x16x32_bf16 v[98:101], v[220:223], v[160:163], v[98:101]
	v_mfma_f32_16x16x32_bf16 v[94:97], v[234:237], v[160:163], v[94:97]
	v_mfma_f32_16x16x32_bf16 v[90:93], v[220:223], v[196:199], v[90:93]
	v_mfma_f32_16x16x32_bf16 v[86:89], v[234:237], v[196:199], v[86:89]
	v_mfma_f32_16x16x32_bf16 v[82:85], v[220:223], v[204:207], v[82:85]
	v_mfma_f32_16x16x32_bf16 v[78:81], v[234:237], v[204:207], v[78:81]
	v_mfma_f32_16x16x32_bf16 v[74:77], v[220:223], v[212:215], v[74:77]
	v_mfma_f32_16x16x32_bf16 v[70:73], v[234:237], v[212:215], v[70:73]
	s_mov_b32 m0, s60
	v_lshl_add_u64 v[164:165], v[238:239], 0, s[36:37]
	s_barrier
	ds_read_b128 v[156:159], v230 offset:49152
	ds_read_b128 v[160:163], v230 offset:50176
	ds_read_b128 v[184:187], v230 offset:51200
	ds_read_b128 v[196:199], v230 offset:52224
	ds_read_b128 v[200:203], v230 offset:53248
	ds_read_b128 v[204:207], v230 offset:54272
	ds_read_b128 v[208:211], v230 offset:55296
	ds_read_b128 v[212:215], v230 offset:56320
	global_load_lds_dwordx4 v[164:165], off
	v_lshl_add_u64 v[164:165], v[240:241], 0, s[36:37]
	s_mov_b32 m0, s61
	s_nop 0
	global_load_lds_dwordx4 v[164:165], off
	s_barrier
	s_waitcnt lgkmcnt(0)
	s_waitcnt lgkmcnt(0)
	v_mfma_f32_16x16x32_bf16 v[66:69], v[140:143], v[156:159], v[66:69]
	v_mfma_f32_16x16x32_bf16 v[62:65], v[148:151], v[156:159], v[62:65]
	v_mfma_f32_16x16x32_bf16 v[58:61], v[140:143], v[184:187], v[58:61]
	v_mfma_f32_16x16x32_bf16 v[54:57], v[148:151], v[184:187], v[54:57]
	v_mfma_f32_16x16x32_bf16 v[50:53], v[140:143], v[200:203], v[50:53]
	v_mfma_f32_16x16x32_bf16 v[46:49], v[148:151], v[200:203], v[46:49]
	v_mfma_f32_16x16x32_bf16 v[42:45], v[140:143], v[208:211], v[42:45]
	v_mfma_f32_16x16x32_bf16 v[38:41], v[148:151], v[208:211], v[38:41]
	v_mfma_f32_16x16x32_bf16 v[66:69], v[144:147], v[160:163], v[66:69]
	v_mfma_f32_16x16x32_bf16 v[62:65], v[152:155], v[160:163], v[62:65]
	v_mfma_f32_16x16x32_bf16 v[58:61], v[144:147], v[196:199], v[58:61]
	v_mfma_f32_16x16x32_bf16 v[54:57], v[152:155], v[196:199], v[54:57]
	v_mfma_f32_16x16x32_bf16 v[50:53], v[144:147], v[204:207], v[50:53]
	v_mfma_f32_16x16x32_bf16 v[46:49], v[152:155], v[204:207], v[46:49]
	v_mfma_f32_16x16x32_bf16 v[42:45], v[144:147], v[212:215], v[42:45]
	v_mfma_f32_16x16x32_bf16 v[38:41], v[152:155], v[212:215], v[38:41]
	s_barrier
	s_add_i32 s10, s10, s52
	v_lshl_add_u64 v[140:141], v[242:243], 0, s[36:37]
	s_mov_b32 m0, s10
	s_nop 0
	global_load_lds_dwordx4 v[140:141], off
	v_lshl_add_u64 v[140:141], v[244:245], 0, s[36:37]
	s_add_i32 m0, s10, 0x2000
	s_nop 0
	global_load_lds_dwordx4 v[140:141], off
	s_waitcnt vmcnt(6)
	s_barrier
	v_mfma_f32_16x16x32_bf16 v[34:37], v[216:219], v[156:159], v[34:37]
	v_mfma_f32_16x16x32_bf16 v[30:33], v[224:227], v[156:159], v[30:33]
	v_mfma_f32_16x16x32_bf16 v[26:29], v[216:219], v[184:187], v[26:29]
	v_mfma_f32_16x16x32_bf16 v[22:25], v[224:227], v[184:187], v[22:25]
	v_mfma_f32_16x16x32_bf16 v[18:21], v[216:219], v[200:203], v[18:21]
	v_mfma_f32_16x16x32_bf16 v[14:17], v[224:227], v[200:203], v[14:17]
	v_mfma_f32_16x16x32_bf16 v[10:13], v[216:219], v[208:211], v[10:13]
	v_mfma_f32_16x16x32_bf16 v[6:9], v[224:227], v[208:211], v[6:9]
	v_mfma_f32_16x16x32_bf16 v[34:37], v[220:223], v[160:163], v[34:37]
	v_mfma_f32_16x16x32_bf16 v[30:33], v[234:237], v[160:163], v[30:33]
	v_mfma_f32_16x16x32_bf16 v[26:29], v[220:223], v[196:199], v[26:29]
	v_mfma_f32_16x16x32_bf16 v[22:25], v[234:237], v[196:199], v[22:25]
	v_mfma_f32_16x16x32_bf16 v[18:21], v[220:223], v[204:207], v[18:21]
	v_mfma_f32_16x16x32_bf16 v[14:17], v[234:237], v[204:207], v[14:17]
	v_mfma_f32_16x16x32_bf16 v[10:13], v[220:223], v[212:215], v[10:13]
	v_mfma_f32_16x16x32_bf16 v[6:9], v[234:237], v[212:215], v[6:9]
	s_add_u32 s6, s6, 0x100
	s_addc_u32 s7, s7, 0
	s_andn2_b64 s[0:1], s[0:1], exec
	s_and_b64 s[10:11], s[8:9], exec
	s_or_b64 s[0:1], s[0:1], s[10:11]
	s_cmp_ge_i32 s69, s57
	s_barrier
	s_cbranch_scc1 .LBB0_1598
	s_mov_b32 s12, s69
	s_branch .LBB0_1594
